# also: qkv Q/K tile epilogue by hand (bias once per tile, rotary tables prefetched, v_permlane32_swap rotary exchange, 16-byte stores), scan items assigned XCD-aware
# speedup vs baseline: 1.0752x; 1.0042x over previous
.LBB0_1107:
	s_or_b64 exec, exec, s[0:1]
	s_add_u32 s62, s84, 0x7a588c0
	s_addc_u32 s63, s85, 0
	s_add_u32 s54, s84, 0x9a988c0
	s_addc_u32 s55, s85, 0
	s_add_u32 s66, s84, 0xdb188c0
	s_addc_u32 s67, s85, 0
	s_add_u32 s58, s84, 0x59108c0
	v_mov_b32_e32 v19, v174
	s_addc_u32 s59, s85, 0
	s_waitcnt lgkmcnt(0)
	s_barrier
	s_cmpk_gt_i32 s2, 0xff
	v_lshl_add_u32 v21, v19, 2, 0
	s_cbranch_scc1 .LBB0_1184
	v_add_u32_e32 v1, 0xffffff00, v19
	v_bfe_u32 v26, v19, 4, 3
	s_movk_i32 s3, 0x7f
	v_and_b32_e32 v18, 15, v19
	v_cmp_lt_u32_e64 s[14:15], s3, v1
	v_mul_u32_u24_e32 v2, 0x270, v26
	v_and_b32_e32 v1, 0xffffff80, v1
	s_movk_i32 s3, 0x80
	v_lshl_add_u32 v27, v2, 2, 0
	v_lshlrev_b32_e32 v2, 4, v18
	v_cmp_ne_u32_e64 s[6:7], s3, v1
	v_and_b32_e32 v1, 0x7f, v19
	v_lshlrev_b32_e32 v28, 1, v26
	v_add_u32_e32 v29, v27, v2
	v_and_b32_e32 v2, 48, v2
	v_lshl_add_u32 v146, v1, 6, 0
	v_or_b32_e32 v1, 0x80, v1
	v_ashrrev_i32_e32 v16, 4, v19
	v_mov_b32_e32 v23, 0
	v_add_u32_e32 v33, v27, v2
	v_lshl_add_u32 v147, v1, 6, 0
	v_lshrrev_b32_e32 v30, 4, v1
	v_mul_u32_u24_e32 v1, 0x880, v26
	v_lshlrev_b32_e32 v2, 1, v18
	v_or_b32_e32 v22, 33, v28
	s_movk_i32 s0, 0x100
	v_ashrrev_i32_e32 v17, 31, v16
	v_lshlrev_b32_e32 v0, 6, v19
	s_mov_b64 s[4:5], 0xff0
	s_add_u32 s34, s82, 0x4080000
	v_or_b32_e32 v34, v1, v2
	v_mov_b64_e32 v[36:37], v[22:23]
	v_mul_u32_u24_e32 v1, 0x880, v30
	v_lshlrev_b32_e32 v22, 7, v26
	s_mov_b64 s[8:9], 0x59114c0
	v_cmp_gt_i32_e64 s[0:1], s0, v19
	v_lshlrev_b32_e32 v20, 2, v18
	v_lshl_add_u64 v[24:25], v[16:17], 0, s[4:5]
	s_mov_b32 s73, 0
	v_cmp_eq_u32_e64 s[4:5], 0, v18
	v_bfe_u32 v31, v19, 2, 2
	s_addc_u32 s35, s83, 0
	v_lshlrev_b32_e32 v32, 12, v26
	s_movk_i32 s40, 0x880
	v_mul_hi_u32_u24_e32 v35, 0x880, v26
	v_mul_hi_u32_u24_e32 v39, 0x880, v30
	v_or_b32_e32 v38, v1, v2
	v_lshl_add_u64 v[40:41], v[22:23], 0, s[8:9]
	v_add_u32_e32 v148, 0, v0
	s_movk_i32 s41, 0x7fff
	s_mov_b32 s3, 1.0
	s_mov_b32 s42, 0xf800000
	v_mov_b32_e32 v149, 0x260
	s_mov_b32 s78, 0x3d800000
	s_mov_b64 s[90:91], 0x22000
	v_mov_b32_e32 v43, 1.0
	v_mov_b32_e32 v150, 0x880
	s_and_b32 s43, s2, 7
	s_lshl_b32 s43, s43, 5
	s_lshr_b32 s44, s2, 3
	s_or_b32 s43, s43, s44
	s_mov_b32 s44, s43
	s_branch .LBB0_1110

.LBB0_1112:
	s_and_b32 s11, s10, 1
	s_mul_i32 s18, s11, 0x4e00
	s_waitcnt vmcnt(0)
	v_lshl_add_u32 v131, s11, 14, v21
	v_lshl_add_u32 v130, v20, 2, s18
	v_mov_b32_e32 v129, s18
	v_lshl_add_u32 v128, v16, 2, s18
	s_add_i32 s10, s10, 1
	ds_read_b128 v[44:47], v130 offset:0
	ds_read_b128 v[48:51], v130 offset:256
	ds_read_b128 v[52:55], v130 offset:512
	ds_read_b128 v[56:59], v130 offset:768
	ds_read_b128 v[60:63], v130 offset:1024
	ds_read_b128 v[64:67], v130 offset:1280
	ds_read_b128 v[68:71], v130 offset:1536
	ds_read_b128 v[72:75], v130 offset:1792
	ds_read_b128 v[76:79], v130 offset:2048
	ds_read_b128 v[80:83], v129 offset:2432
	ds_read_b128 v[84:87], v129 offset:2448
	ds_read_b32 v89, v128 offset:2304
	ds_read_b32 v91, v128 offset:2368
	ds_read_b128 v[196:199], v130 offset:2496
	ds_read_b128 v[200:203], v130 offset:2752
	ds_read_b128 v[204:207], v130 offset:3008
	ds_read_b128 v[208:211], v130 offset:3264
	ds_read_b128 v[212:215], v130 offset:3520
	ds_read_b128 v[216:219], v130 offset:3776
	ds_read_b128 v[220:223], v130 offset:4032
	ds_read_b128 v[224:227], v130 offset:4288
	ds_read_b128 v[228:231], v130 offset:4544
	ds_read_b128 v[232:235], v129 offset:4928
	ds_read_b128 v[236:239], v129 offset:4944
	ds_read_b32 v241, v128 offset:4800
	ds_read_b32 v243, v128 offset:4864
	s_waitcnt lgkmcnt(13)
	v_pk_mul_f32 v[4:5], v[0:1], v[44:45]
	v_pk_mul_f32 v[6:7], v[0:1], v[48:49]
	v_pk_fma_f32 v[4:5], v[2:3], v[46:47], v[4:5]
	v_pk_fma_f32 v[6:7], v[2:3], v[50:51], v[6:7]
	v_add_f32_e32 v22, v4, v5
	v_add_f32_e32 v42, v6, v7
	v_pk_mul_f32 v[8:9], v[0:1], v[52:53]
	v_add_f32_dpp v22, v22, v22 quad_perm:[1,0,3,2] row_mask:0xf bank_mask:0xf bound_ctrl:1
	v_add_f32_dpp v42, v42, v42 quad_perm:[1,0,3,2] row_mask:0xf bank_mask:0xf bound_ctrl:1
	v_pk_mul_f32 v[10:11], v[2:3], v[54:55]
	v_add_f32_dpp v22, v22, v22 quad_perm:[2,3,0,1] row_mask:0xf bank_mask:0xf bound_ctrl:1
	v_add_f32_dpp v42, v42, v42 quad_perm:[2,3,0,1] row_mask:0xf bank_mask:0xf bound_ctrl:1
	v_pk_mul_f32 v[12:13], v[0:1], v[72:73]
	v_add_f32_dpp v22, v22, v22 row_ror:4 row_mask:0xf bank_mask:0xf bound_ctrl:1
	v_add_f32_dpp v42, v42, v42 row_ror:4 row_mask:0xf bank_mask:0xf bound_ctrl:1
	v_pk_mul_f32 v[14:15], v[0:1], v[76:77]
	v_add_f32_dpp v88, v22, v22 row_ror:8 row_mask:0xf bank_mask:0xf bound_ctrl:1
	v_add_f32_dpp v42, v42, v42 row_ror:8 row_mask:0xf bank_mask:0xf bound_ctrl:1
	v_pk_fma_f32 v[8:9], v[88:89], v[60:61], v[8:9] op_sel:[1,0,0] op_sel_hi:[1,1,1]
	v_pk_fma_f32 v[10:11], v[88:89], v[62:63], v[10:11] op_sel:[1,0,0] op_sel_hi:[1,1,1]
	v_fma_f32 v4, v88, v80, v42
	v_pk_fma_f32 v[8:9], v[90:91], v[68:69], v[8:9] op_sel:[1,0,0] op_sel_hi:[1,1,1]
	v_fma_f32 v90, v89, v81, v4
	v_pk_fma_f32 v[10:11], v[90:91], v[70:71], v[10:11] op_sel:[1,0,0] op_sel_hi:[1,1,1]
	v_pk_fma_f32 v[12:13], v[2:3], v[74:75], v[12:13]
	v_pk_fma_f32 v[14:15], v[2:3], v[78:79], v[14:15]
	v_pk_fma_f32 v[0:1], v[88:89], v[56:57], v[8:9] op_sel:[0,0,0] op_sel_hi:[0,1,1]
	v_pk_fma_f32 v[2:3], v[88:89], v[58:59], v[10:11] op_sel:[0,0,0] op_sel_hi:[0,1,1]
	v_pk_fma_f32 v[0:1], v[90:91], v[64:65], v[0:1] op_sel:[0,0,0] op_sel_hi:[0,1,1]
	v_pk_fma_f32 v[2:3], v[90:91], v[66:67], v[2:3] op_sel:[0,0,0] op_sel_hi:[0,1,1]
	v_pk_fma_f32 v[12:13], v[88:89], v[82:83], v[12:13]
	v_pk_fma_f32 v[14:15], v[90:91], v[86:87], v[14:15]
	v_pk_fma_f32 v[14:15], v[88:89], v[84:85], v[14:15]
	v_add_f32_e32 v6, v12, v13
	v_add_f32_e32 v7, v14, v15
	ds_write2st64_b32 v131, v6, v7 offset0:156 offset1:160
	ds_read_b128 v[44:47], v130 offset:4992
	ds_read_b128 v[48:51], v130 offset:5248
	ds_read_b128 v[52:55], v130 offset:5504
	ds_read_b128 v[56:59], v130 offset:5760
	ds_read_b128 v[60:63], v130 offset:6016
	ds_read_b128 v[64:67], v130 offset:6272
	ds_read_b128 v[68:71], v130 offset:6528
	ds_read_b128 v[72:75], v130 offset:6784
	ds_read_b128 v[76:79], v130 offset:7040
	ds_read_b128 v[80:83], v129 offset:7424
	ds_read_b128 v[84:87], v129 offset:7440
	ds_read_b32 v89, v128 offset:7296
	ds_read_b32 v91, v128 offset:7360
	s_waitcnt lgkmcnt(13)
	v_pk_mul_f32 v[4:5], v[0:1], v[196:197]
	v_pk_mul_f32 v[6:7], v[0:1], v[200:201]
	v_pk_fma_f32 v[4:5], v[2:3], v[198:199], v[4:5]
	v_pk_fma_f32 v[6:7], v[2:3], v[202:203], v[6:7]
	v_add_f32_e32 v22, v4, v5
	v_add_f32_e32 v42, v6, v7
	v_pk_mul_f32 v[8:9], v[0:1], v[204:205]
	v_add_f32_dpp v22, v22, v22 quad_perm:[1,0,3,2] row_mask:0xf bank_mask:0xf bound_ctrl:1
	v_add_f32_dpp v42, v42, v42 quad_perm:[1,0,3,2] row_mask:0xf bank_mask:0xf bound_ctrl:1
	v_pk_mul_f32 v[10:11], v[2:3], v[206:207]
	v_add_f32_dpp v22, v22, v22 quad_perm:[2,3,0,1] row_mask:0xf bank_mask:0xf bound_ctrl:1
	v_add_f32_dpp v42, v42, v42 quad_perm:[2,3,0,1] row_mask:0xf bank_mask:0xf bound_ctrl:1
	v_pk_mul_f32 v[12:13], v[0:1], v[224:225]
	v_add_f32_dpp v22, v22, v22 row_ror:4 row_mask:0xf bank_mask:0xf bound_ctrl:1
	v_add_f32_dpp v42, v42, v42 row_ror:4 row_mask:0xf bank_mask:0xf bound_ctrl:1
	v_pk_mul_f32 v[14:15], v[0:1], v[228:229]
	v_add_f32_dpp v240, v22, v22 row_ror:8 row_mask:0xf bank_mask:0xf bound_ctrl:1
	v_add_f32_dpp v42, v42, v42 row_ror:8 row_mask:0xf bank_mask:0xf bound_ctrl:1
	v_pk_fma_f32 v[8:9], v[240:241], v[212:213], v[8:9] op_sel:[1,0,0] op_sel_hi:[1,1,1]
	v_pk_fma_f32 v[10:11], v[240:241], v[214:215], v[10:11] op_sel:[1,0,0] op_sel_hi:[1,1,1]
	v_fma_f32 v4, v240, v232, v42
	v_pk_fma_f32 v[8:9], v[242:243], v[220:221], v[8:9] op_sel:[1,0,0] op_sel_hi:[1,1,1]
	v_fma_f32 v242, v241, v233, v4
	v_pk_fma_f32 v[10:11], v[242:243], v[222:223], v[10:11] op_sel:[1,0,0] op_sel_hi:[1,1,1]
	v_pk_fma_f32 v[12:13], v[2:3], v[226:227], v[12:13]
	v_pk_fma_f32 v[14:15], v[2:3], v[230:231], v[14:15]
	v_pk_fma_f32 v[0:1], v[240:241], v[208:209], v[8:9] op_sel:[0,0,0] op_sel_hi:[0,1,1]
	v_pk_fma_f32 v[2:3], v[240:241], v[210:211], v[10:11] op_sel:[0,0,0] op_sel_hi:[0,1,1]
	v_pk_fma_f32 v[0:1], v[242:243], v[216:217], v[0:1] op_sel:[0,0,0] op_sel_hi:[0,1,1]
	v_pk_fma_f32 v[2:3], v[242:243], v[218:219], v[2:3] op_sel:[0,0,0] op_sel_hi:[0,1,1]
	v_pk_fma_f32 v[12:13], v[240:241], v[234:235], v[12:13]
	v_pk_fma_f32 v[14:15], v[242:243], v[238:239], v[14:15]
	v_pk_fma_f32 v[14:15], v[240:241], v[236:237], v[14:15]
	v_add_f32_e32 v6, v12, v13
	v_add_f32_e32 v7, v14, v15
	ds_write2st64_b32 v131, v6, v7 offset0:164 offset1:168
	ds_read_b128 v[196:199], v130 offset:7488
	ds_read_b128 v[200:203], v130 offset:7744
	ds_read_b128 v[204:207], v130 offset:8000
	ds_read_b128 v[208:211], v130 offset:8256
	ds_read_b128 v[212:215], v130 offset:8512
	ds_read_b128 v[216:219], v130 offset:8768
	ds_read_b128 v[220:223], v130 offset:9024
	ds_read_b128 v[224:227], v130 offset:9280
	ds_read_b128 v[228:231], v130 offset:9536
	ds_read_b128 v[232:235], v129 offset:9920
	ds_read_b128 v[236:239], v129 offset:9936
	ds_read_b32 v241, v128 offset:9792
	ds_read_b32 v243, v128 offset:9856
	s_waitcnt lgkmcnt(13)
	v_pk_mul_f32 v[4:5], v[0:1], v[44:45]
	v_pk_mul_f32 v[6:7], v[0:1], v[48:49]
	v_pk_fma_f32 v[4:5], v[2:3], v[46:47], v[4:5]
	v_pk_fma_f32 v[6:7], v[2:3], v[50:51], v[6:7]
	v_add_f32_e32 v22, v4, v5
	v_add_f32_e32 v42, v6, v7
	v_pk_mul_f32 v[8:9], v[0:1], v[52:53]
	v_add_f32_dpp v22, v22, v22 quad_perm:[1,0,3,2] row_mask:0xf bank_mask:0xf bound_ctrl:1
	v_add_f32_dpp v42, v42, v42 quad_perm:[1,0,3,2] row_mask:0xf bank_mask:0xf bound_ctrl:1
	v_pk_mul_f32 v[10:11], v[2:3], v[54:55]
	v_add_f32_dpp v22, v22, v22 quad_perm:[2,3,0,1] row_mask:0xf bank_mask:0xf bound_ctrl:1
	v_add_f32_dpp v42, v42, v42 quad_perm:[2,3,0,1] row_mask:0xf bank_mask:0xf bound_ctrl:1
	v_pk_mul_f32 v[12:13], v[0:1], v[72:73]
	v_add_f32_dpp v22, v22, v22 row_ror:4 row_mask:0xf bank_mask:0xf bound_ctrl:1
	v_add_f32_dpp v42, v42, v42 row_ror:4 row_mask:0xf bank_mask:0xf bound_ctrl:1
	v_pk_mul_f32 v[14:15], v[0:1], v[76:77]
	v_add_f32_dpp v88, v22, v22 row_ror:8 row_mask:0xf bank_mask:0xf bound_ctrl:1
	v_add_f32_dpp v42, v42, v42 row_ror:8 row_mask:0xf bank_mask:0xf bound_ctrl:1
	v_pk_fma_f32 v[8:9], v[88:89], v[60:61], v[8:9] op_sel:[1,0,0] op_sel_hi:[1,1,1]
	v_pk_fma_f32 v[10:11], v[88:89], v[62:63], v[10:11] op_sel:[1,0,0] op_sel_hi:[1,1,1]
	v_fma_f32 v4, v88, v80, v42
	v_pk_fma_f32 v[8:9], v[90:91], v[68:69], v[8:9] op_sel:[1,0,0] op_sel_hi:[1,1,1]
	v_fma_f32 v90, v89, v81, v4
	v_pk_fma_f32 v[10:11], v[90:91], v[70:71], v[10:11] op_sel:[1,0,0] op_sel_hi:[1,1,1]
	v_pk_fma_f32 v[12:13], v[2:3], v[74:75], v[12:13]
	v_pk_fma_f32 v[14:15], v[2:3], v[78:79], v[14:15]
	v_pk_fma_f32 v[0:1], v[88:89], v[56:57], v[8:9] op_sel:[0,0,0] op_sel_hi:[0,1,1]
	v_pk_fma_f32 v[2:3], v[88:89], v[58:59], v[10:11] op_sel:[0,0,0] op_sel_hi:[0,1,1]
	v_pk_fma_f32 v[0:1], v[90:91], v[64:65], v[0:1] op_sel:[0,0,0] op_sel_hi:[0,1,1]
	v_pk_fma_f32 v[2:3], v[90:91], v[66:67], v[2:3] op_sel:[0,0,0] op_sel_hi:[0,1,1]
	v_pk_fma_f32 v[12:13], v[88:89], v[82:83], v[12:13]
	v_pk_fma_f32 v[14:15], v[90:91], v[86:87], v[14:15]
	v_pk_fma_f32 v[14:15], v[88:89], v[84:85], v[14:15]
	v_add_f32_e32 v6, v12, v13
	v_add_f32_e32 v7, v14, v15
	ds_write2st64_b32 v131, v6, v7 offset0:172 offset1:176
	ds_read_b128 v[44:47], v130 offset:9984
	ds_read_b128 v[48:51], v130 offset:10240
	ds_read_b128 v[52:55], v130 offset:10496
	ds_read_b128 v[56:59], v130 offset:10752
	ds_read_b128 v[60:63], v130 offset:11008
	ds_read_b128 v[64:67], v130 offset:11264
	ds_read_b128 v[68:71], v130 offset:11520
	ds_read_b128 v[72:75], v130 offset:11776
	ds_read_b128 v[76:79], v130 offset:12032
	ds_read_b128 v[80:83], v129 offset:12416
	ds_read_b128 v[84:87], v129 offset:12432
	ds_read_b32 v89, v128 offset:12288
	ds_read_b32 v91, v128 offset:12352
	s_waitcnt lgkmcnt(13)
	v_pk_mul_f32 v[4:5], v[0:1], v[196:197]
	v_pk_mul_f32 v[6:7], v[0:1], v[200:201]
	v_pk_fma_f32 v[4:5], v[2:3], v[198:199], v[4:5]
	v_pk_fma_f32 v[6:7], v[2:3], v[202:203], v[6:7]
	v_add_f32_e32 v22, v4, v5
	v_add_f32_e32 v42, v6, v7
	v_pk_mul_f32 v[8:9], v[0:1], v[204:205]
	v_add_f32_dpp v22, v22, v22 quad_perm:[1,0,3,2] row_mask:0xf bank_mask:0xf bound_ctrl:1
	v_add_f32_dpp v42, v42, v42 quad_perm:[1,0,3,2] row_mask:0xf bank_mask:0xf bound_ctrl:1
	v_pk_mul_f32 v[10:11], v[2:3], v[206:207]
	v_add_f32_dpp v22, v22, v22 quad_perm:[2,3,0,1] row_mask:0xf bank_mask:0xf bound_ctrl:1
	v_add_f32_dpp v42, v42, v42 quad_perm:[2,3,0,1] row_mask:0xf bank_mask:0xf bound_ctrl:1
	v_pk_mul_f32 v[12:13], v[0:1], v[224:225]
	v_add_f32_dpp v22, v22, v22 row_ror:4 row_mask:0xf bank_mask:0xf bound_ctrl:1
	v_add_f32_dpp v42, v42, v42 row_ror:4 row_mask:0xf bank_mask:0xf bound_ctrl:1
	v_pk_mul_f32 v[14:15], v[0:1], v[228:229]
	v_add_f32_dpp v240, v22, v22 row_ror:8 row_mask:0xf bank_mask:0xf bound_ctrl:1
	v_add_f32_dpp v42, v42, v42 row_ror:8 row_mask:0xf bank_mask:0xf bound_ctrl:1
	v_pk_fma_f32 v[8:9], v[240:241], v[212:213], v[8:9] op_sel:[1,0,0] op_sel_hi:[1,1,1]
	v_pk_fma_f32 v[10:11], v[240:241], v[214:215], v[10:11] op_sel:[1,0,0] op_sel_hi:[1,1,1]
	v_fma_f32 v4, v240, v232, v42
	v_pk_fma_f32 v[8:9], v[242:243], v[220:221], v[8:9] op_sel:[1,0,0] op_sel_hi:[1,1,1]
	v_fma_f32 v242, v241, v233, v4
	v_pk_fma_f32 v[10:11], v[242:243], v[222:223], v[10:11] op_sel:[1,0,0] op_sel_hi:[1,1,1]
	v_pk_fma_f32 v[12:13], v[2:3], v[226:227], v[12:13]
	v_pk_fma_f32 v[14:15], v[2:3], v[230:231], v[14:15]
	v_pk_fma_f32 v[0:1], v[240:241], v[208:209], v[8:9] op_sel:[0,0,0] op_sel_hi:[0,1,1]
	v_pk_fma_f32 v[2:3], v[240:241], v[210:211], v[10:11] op_sel:[0,0,0] op_sel_hi:[0,1,1]
	v_pk_fma_f32 v[0:1], v[242:243], v[216:217], v[0:1] op_sel:[0,0,0] op_sel_hi:[0,1,1]
	v_pk_fma_f32 v[2:3], v[242:243], v[218:219], v[2:3] op_sel:[0,0,0] op_sel_hi:[0,1,1]
	v_pk_fma_f32 v[12:13], v[240:241], v[234:235], v[12:13]
	v_pk_fma_f32 v[14:15], v[242:243], v[238:239], v[14:15]
	v_pk_fma_f32 v[14:15], v[240:241], v[236:237], v[14:15]
	v_add_f32_e32 v6, v12, v13
	v_add_f32_e32 v7, v14, v15
	ds_write2st64_b32 v131, v6, v7 offset0:180 offset1:184
	ds_read_b128 v[196:199], v130 offset:12480
	ds_read_b128 v[200:203], v130 offset:12736
	ds_read_b128 v[204:207], v130 offset:12992
	ds_read_b128 v[208:211], v130 offset:13248
	ds_read_b128 v[212:215], v130 offset:13504
	ds_read_b128 v[216:219], v130 offset:13760
	ds_read_b128 v[220:223], v130 offset:14016
	ds_read_b128 v[224:227], v130 offset:14272
	ds_read_b128 v[228:231], v130 offset:14528
	ds_read_b128 v[232:235], v129 offset:14912
	ds_read_b128 v[236:239], v129 offset:14928
	ds_read_b32 v241, v128 offset:14784
	ds_read_b32 v243, v128 offset:14848
	s_waitcnt lgkmcnt(13)
	v_pk_mul_f32 v[4:5], v[0:1], v[44:45]
	v_pk_mul_f32 v[6:7], v[0:1], v[48:49]
	v_pk_fma_f32 v[4:5], v[2:3], v[46:47], v[4:5]
	v_pk_fma_f32 v[6:7], v[2:3], v[50:51], v[6:7]
	v_add_f32_e32 v22, v4, v5
	v_add_f32_e32 v42, v6, v7
	v_pk_mul_f32 v[8:9], v[0:1], v[52:53]
	v_add_f32_dpp v22, v22, v22 quad_perm:[1,0,3,2] row_mask:0xf bank_mask:0xf bound_ctrl:1
	v_add_f32_dpp v42, v42, v42 quad_perm:[1,0,3,2] row_mask:0xf bank_mask:0xf bound_ctrl:1
	v_pk_mul_f32 v[10:11], v[2:3], v[54:55]
	v_add_f32_dpp v22, v22, v22 quad_perm:[2,3,0,1] row_mask:0xf bank_mask:0xf bound_ctrl:1
	v_add_f32_dpp v42, v42, v42 quad_perm:[2,3,0,1] row_mask:0xf bank_mask:0xf bound_ctrl:1
	v_pk_mul_f32 v[12:13], v[0:1], v[72:73]
	v_add_f32_dpp v22, v22, v22 row_ror:4 row_mask:0xf bank_mask:0xf bound_ctrl:1
	v_add_f32_dpp v42, v42, v42 row_ror:4 row_mask:0xf bank_mask:0xf bound_ctrl:1
	v_pk_mul_f32 v[14:15], v[0:1], v[76:77]
	v_add_f32_dpp v88, v22, v22 row_ror:8 row_mask:0xf bank_mask:0xf bound_ctrl:1
	v_add_f32_dpp v42, v42, v42 row_ror:8 row_mask:0xf bank_mask:0xf bound_ctrl:1
	v_pk_fma_f32 v[8:9], v[88:89], v[60:61], v[8:9] op_sel:[1,0,0] op_sel_hi:[1,1,1]
	v_pk_fma_f32 v[10:11], v[88:89], v[62:63], v[10:11] op_sel:[1,0,0] op_sel_hi:[1,1,1]
	v_fma_f32 v4, v88, v80, v42
	v_pk_fma_f32 v[8:9], v[90:91], v[68:69], v[8:9] op_sel:[1,0,0] op_sel_hi:[1,1,1]
	v_fma_f32 v90, v89, v81, v4
	v_pk_fma_f32 v[10:11], v[90:91], v[70:71], v[10:11] op_sel:[1,0,0] op_sel_hi:[1,1,1]
	v_pk_fma_f32 v[12:13], v[2:3], v[74:75], v[12:13]
	v_pk_fma_f32 v[14:15], v[2:3], v[78:79], v[14:15]
	v_pk_fma_f32 v[0:1], v[88:89], v[56:57], v[8:9] op_sel:[0,0,0] op_sel_hi:[0,1,1]
	v_pk_fma_f32 v[2:3], v[88:89], v[58:59], v[10:11] op_sel:[0,0,0] op_sel_hi:[0,1,1]
	v_pk_fma_f32 v[0:1], v[90:91], v[64:65], v[0:1] op_sel:[0,0,0] op_sel_hi:[0,1,1]
	v_pk_fma_f32 v[2:3], v[90:91], v[66:67], v[2:3] op_sel:[0,0,0] op_sel_hi:[0,1,1]
	v_pk_fma_f32 v[12:13], v[88:89], v[82:83], v[12:13]
	v_pk_fma_f32 v[14:15], v[90:91], v[86:87], v[14:15]
	v_pk_fma_f32 v[14:15], v[88:89], v[84:85], v[14:15]
	v_add_f32_e32 v6, v12, v13
	v_add_f32_e32 v7, v14, v15
	ds_write2st64_b32 v131, v6, v7 offset0:188 offset1:192
	ds_read_b128 v[44:47], v130 offset:14976
	ds_read_b128 v[48:51], v130 offset:15232
	ds_read_b128 v[52:55], v130 offset:15488
	ds_read_b128 v[56:59], v130 offset:15744
	ds_read_b128 v[60:63], v130 offset:16000
	ds_read_b128 v[64:67], v130 offset:16256
	ds_read_b128 v[68:71], v130 offset:16512
	ds_read_b128 v[72:75], v130 offset:16768
	ds_read_b128 v[76:79], v130 offset:17024
	ds_read_b128 v[80:83], v129 offset:17408
	ds_read_b128 v[84:87], v129 offset:17424
	ds_read_b32 v89, v128 offset:17280
	ds_read_b32 v91, v128 offset:17344
	s_waitcnt lgkmcnt(13)
	v_pk_mul_f32 v[4:5], v[0:1], v[196:197]
	v_pk_mul_f32 v[6:7], v[0:1], v[200:201]
	v_pk_fma_f32 v[4:5], v[2:3], v[198:199], v[4:5]
	v_pk_fma_f32 v[6:7], v[2:3], v[202:203], v[6:7]
	v_add_f32_e32 v22, v4, v5
	v_add_f32_e32 v42, v6, v7
	v_pk_mul_f32 v[8:9], v[0:1], v[204:205]
	v_add_f32_dpp v22, v22, v22 quad_perm:[1,0,3,2] row_mask:0xf bank_mask:0xf bound_ctrl:1
	v_add_f32_dpp v42, v42, v42 quad_perm:[1,0,3,2] row_mask:0xf bank_mask:0xf bound_ctrl:1
	v_pk_mul_f32 v[10:11], v[2:3], v[206:207]
	v_add_f32_dpp v22, v22, v22 quad_perm:[2,3,0,1] row_mask:0xf bank_mask:0xf bound_ctrl:1
	v_add_f32_dpp v42, v42, v42 quad_perm:[2,3,0,1] row_mask:0xf bank_mask:0xf bound_ctrl:1
	v_pk_mul_f32 v[12:13], v[0:1], v[224:225]
	v_add_f32_dpp v22, v22, v22 row_ror:4 row_mask:0xf bank_mask:0xf bound_ctrl:1
	v_add_f32_dpp v42, v42, v42 row_ror:4 row_mask:0xf bank_mask:0xf bound_ctrl:1
	v_pk_mul_f32 v[14:15], v[0:1], v[228:229]
	v_add_f32_dpp v240, v22, v22 row_ror:8 row_mask:0xf bank_mask:0xf bound_ctrl:1
	v_add_f32_dpp v42, v42, v42 row_ror:8 row_mask:0xf bank_mask:0xf bound_ctrl:1
	v_pk_fma_f32 v[8:9], v[240:241], v[212:213], v[8:9] op_sel:[1,0,0] op_sel_hi:[1,1,1]
	v_pk_fma_f32 v[10:11], v[240:241], v[214:215], v[10:11] op_sel:[1,0,0] op_sel_hi:[1,1,1]
	v_fma_f32 v4, v240, v232, v42
	v_pk_fma_f32 v[8:9], v[242:243], v[220:221], v[8:9] op_sel:[1,0,0] op_sel_hi:[1,1,1]
	v_fma_f32 v242, v241, v233, v4
	v_pk_fma_f32 v[10:11], v[242:243], v[222:223], v[10:11] op_sel:[1,0,0] op_sel_hi:[1,1,1]
	v_pk_fma_f32 v[12:13], v[2:3], v[226:227], v[12:13]
	v_pk_fma_f32 v[14:15], v[2:3], v[230:231], v[14:15]
	v_pk_fma_f32 v[0:1], v[240:241], v[208:209], v[8:9] op_sel:[0,0,0] op_sel_hi:[0,1,1]
	v_pk_fma_f32 v[2:3], v[240:241], v[210:211], v[10:11] op_sel:[0,0,0] op_sel_hi:[0,1,1]
	v_pk_fma_f32 v[0:1], v[242:243], v[216:217], v[0:1] op_sel:[0,0,0] op_sel_hi:[0,1,1]
	v_pk_fma_f32 v[2:3], v[242:243], v[218:219], v[2:3] op_sel:[0,0,0] op_sel_hi:[0,1,1]
	v_pk_fma_f32 v[12:13], v[240:241], v[234:235], v[12:13]
	v_pk_fma_f32 v[14:15], v[242:243], v[238:239], v[14:15]
	v_pk_fma_f32 v[14:15], v[240:241], v[236:237], v[14:15]
	v_add_f32_e32 v6, v12, v13
	v_add_f32_e32 v7, v14, v15
	ds_write2st64_b32 v131, v6, v7 offset0:196 offset1:200
	ds_read_b128 v[196:199], v130 offset:17472
	ds_read_b128 v[200:203], v130 offset:17728
	ds_read_b128 v[204:207], v130 offset:17984
	ds_read_b128 v[208:211], v130 offset:18240
	ds_read_b128 v[212:215], v130 offset:18496
	ds_read_b128 v[216:219], v130 offset:18752
	ds_read_b128 v[220:223], v130 offset:19008
	ds_read_b128 v[224:227], v130 offset:19264
	ds_read_b128 v[228:231], v130 offset:19520
	ds_read_b128 v[232:235], v129 offset:19904
	ds_read_b128 v[236:239], v129 offset:19920
	ds_read_b32 v241, v128 offset:19776
	ds_read_b32 v243, v128 offset:19840
	s_waitcnt lgkmcnt(13)
	v_pk_mul_f32 v[4:5], v[0:1], v[44:45]
	v_pk_mul_f32 v[6:7], v[0:1], v[48:49]
	v_pk_fma_f32 v[4:5], v[2:3], v[46:47], v[4:5]
	v_pk_fma_f32 v[6:7], v[2:3], v[50:51], v[6:7]
	v_add_f32_e32 v22, v4, v5
	v_add_f32_e32 v42, v6, v7
	v_pk_mul_f32 v[8:9], v[0:1], v[52:53]
	v_add_f32_dpp v22, v22, v22 quad_perm:[1,0,3,2] row_mask:0xf bank_mask:0xf bound_ctrl:1
	v_add_f32_dpp v42, v42, v42 quad_perm:[1,0,3,2] row_mask:0xf bank_mask:0xf bound_ctrl:1
	v_pk_mul_f32 v[10:11], v[2:3], v[54:55]
	v_add_f32_dpp v22, v22, v22 quad_perm:[2,3,0,1] row_mask:0xf bank_mask:0xf bound_ctrl:1
	v_add_f32_dpp v42, v42, v42 quad_perm:[2,3,0,1] row_mask:0xf bank_mask:0xf bound_ctrl:1
	v_pk_mul_f32 v[12:13], v[0:1], v[72:73]
	v_add_f32_dpp v22, v22, v22 row_ror:4 row_mask:0xf bank_mask:0xf bound_ctrl:1
	v_add_f32_dpp v42, v42, v42 row_ror:4 row_mask:0xf bank_mask:0xf bound_ctrl:1
	v_pk_mul_f32 v[14:15], v[0:1], v[76:77]
	v_add_f32_dpp v88, v22, v22 row_ror:8 row_mask:0xf bank_mask:0xf bound_ctrl:1
	v_add_f32_dpp v42, v42, v42 row_ror:8 row_mask:0xf bank_mask:0xf bound_ctrl:1
	v_pk_fma_f32 v[8:9], v[88:89], v[60:61], v[8:9] op_sel:[1,0,0] op_sel_hi:[1,1,1]
	v_pk_fma_f32 v[10:11], v[88:89], v[62:63], v[10:11] op_sel:[1,0,0] op_sel_hi:[1,1,1]
	v_fma_f32 v4, v88, v80, v42
	v_pk_fma_f32 v[8:9], v[90:91], v[68:69], v[8:9] op_sel:[1,0,0] op_sel_hi:[1,1,1]
	v_fma_f32 v90, v89, v81, v4
	v_pk_fma_f32 v[10:11], v[90:91], v[70:71], v[10:11] op_sel:[1,0,0] op_sel_hi:[1,1,1]
	v_pk_fma_f32 v[12:13], v[2:3], v[74:75], v[12:13]
	v_pk_fma_f32 v[14:15], v[2:3], v[78:79], v[14:15]
	v_pk_fma_f32 v[0:1], v[88:89], v[56:57], v[8:9] op_sel:[0,0,0] op_sel_hi:[0,1,1]
	v_pk_fma_f32 v[2:3], v[88:89], v[58:59], v[10:11] op_sel:[0,0,0] op_sel_hi:[0,1,1]
	v_pk_fma_f32 v[0:1], v[90:91], v[64:65], v[0:1] op_sel:[0,0,0] op_sel_hi:[0,1,1]
	v_pk_fma_f32 v[2:3], v[90:91], v[66:67], v[2:3] op_sel:[0,0,0] op_sel_hi:[0,1,1]
	v_pk_fma_f32 v[12:13], v[88:89], v[82:83], v[12:13]
	v_pk_fma_f32 v[14:15], v[90:91], v[86:87], v[14:15]
	v_pk_fma_f32 v[14:15], v[88:89], v[84:85], v[14:15]
	v_add_f32_e32 v6, v12, v13
	v_add_f32_e32 v7, v14, v15
	ds_write2st64_b32 v131, v6, v7 offset0:204 offset1:208
	s_waitcnt lgkmcnt(0)
	v_pk_mul_f32 v[4:5], v[0:1], v[196:197]
	v_pk_mul_f32 v[6:7], v[0:1], v[200:201]
	v_pk_fma_f32 v[4:5], v[2:3], v[198:199], v[4:5]
	v_pk_fma_f32 v[6:7], v[2:3], v[202:203], v[6:7]
	v_add_f32_e32 v22, v4, v5
	v_add_f32_e32 v42, v6, v7
	v_pk_mul_f32 v[8:9], v[0:1], v[204:205]
	v_add_f32_dpp v22, v22, v22 quad_perm:[1,0,3,2] row_mask:0xf bank_mask:0xf bound_ctrl:1
	v_add_f32_dpp v42, v42, v42 quad_perm:[1,0,3,2] row_mask:0xf bank_mask:0xf bound_ctrl:1
	v_pk_mul_f32 v[10:11], v[2:3], v[206:207]
	v_add_f32_dpp v22, v22, v22 quad_perm:[2,3,0,1] row_mask:0xf bank_mask:0xf bound_ctrl:1
	v_add_f32_dpp v42, v42, v42 quad_perm:[2,3,0,1] row_mask:0xf bank_mask:0xf bound_ctrl:1
	v_pk_mul_f32 v[12:13], v[0:1], v[224:225]
	v_add_f32_dpp v22, v22, v22 row_ror:4 row_mask:0xf bank_mask:0xf bound_ctrl:1
	v_add_f32_dpp v42, v42, v42 row_ror:4 row_mask:0xf bank_mask:0xf bound_ctrl:1
	v_pk_mul_f32 v[14:15], v[0:1], v[228:229]
	v_add_f32_dpp v240, v22, v22 row_ror:8 row_mask:0xf bank_mask:0xf bound_ctrl:1
	v_add_f32_dpp v42, v42, v42 row_ror:8 row_mask:0xf bank_mask:0xf bound_ctrl:1
	v_pk_fma_f32 v[8:9], v[240:241], v[212:213], v[8:9] op_sel:[1,0,0] op_sel_hi:[1,1,1]
	v_pk_fma_f32 v[10:11], v[240:241], v[214:215], v[10:11] op_sel:[1,0,0] op_sel_hi:[1,1,1]
	v_fma_f32 v4, v240, v232, v42
	v_pk_fma_f32 v[8:9], v[242:243], v[220:221], v[8:9] op_sel:[1,0,0] op_sel_hi:[1,1,1]
	v_fma_f32 v242, v241, v233, v4
	v_pk_fma_f32 v[10:11], v[242:243], v[222:223], v[10:11] op_sel:[1,0,0] op_sel_hi:[1,1,1]
	v_pk_fma_f32 v[12:13], v[2:3], v[226:227], v[12:13]
	v_pk_fma_f32 v[14:15], v[2:3], v[230:231], v[14:15]
	v_pk_fma_f32 v[0:1], v[240:241], v[208:209], v[8:9] op_sel:[0,0,0] op_sel_hi:[0,1,1]
	v_pk_fma_f32 v[2:3], v[240:241], v[210:211], v[10:11] op_sel:[0,0,0] op_sel_hi:[0,1,1]
	v_pk_fma_f32 v[0:1], v[242:243], v[216:217], v[0:1] op_sel:[0,0,0] op_sel_hi:[0,1,1]
	v_pk_fma_f32 v[2:3], v[242:243], v[218:219], v[2:3] op_sel:[0,0,0] op_sel_hi:[0,1,1]
	v_pk_fma_f32 v[12:13], v[240:241], v[234:235], v[12:13]
	v_pk_fma_f32 v[14:15], v[242:243], v[238:239], v[14:15]
	v_pk_fma_f32 v[14:15], v[240:241], v[236:237], v[14:15]
	v_add_f32_e32 v6, v12, v13
	v_add_f32_e32 v7, v14, v15
	ds_write2st64_b32 v131, v6, v7 offset0:212 offset1:216
.Lscw_a:
	s_waitcnt lgkmcnt(0)
	s_barrier
.Lscw_b:
	s_cmpk_eq_i32 s10, 0x100
	s_cbranch_scc0 .LBB0_1112
	ds_read_b128 v[4:7], v148 offset:56320
	ds_read_b128 v[8:11], v148 offset:56336
	ds_read_b128 v[12:15], v148 offset:56352
	ds_read_b128 v[44:47], v148 offset:56368
	v_lshlrev_b32_e32 v22, 1, v18
	s_waitcnt lgkmcnt(3)
	v_mov_b32_e32 v48, v5
	v_mov_b32_e32 v49, v6
	s_waitcnt lgkmcnt(2)
	v_mov_b32_e32 v50, v9
	v_mov_b32_e32 v51, v10
	v_mov_b32_e32 v5, v7
	v_mov_b32_e32 v9, v11
	v_pk_add_f32 v[4:5], v[48:49], v[4:5]
	v_pk_add_f32 v[6:7], v[50:51], v[8:9]
	s_waitcnt lgkmcnt(1)
	v_mov_b32_e32 v8, v13
	v_mov_b32_e32 v10, v15
	v_pk_add_f32 v[4:5], v[4:5], v[4:5] op_sel:[0,1] op_sel_hi:[1,0]
	v_pk_add_f32 v[6:7], v[6:7], v[6:7] op_sel:[0,1] op_sel_hi:[1,0]
	v_pk_add_f32 v[8:9], v[12:13], v[8:9]
	v_pk_add_f32 v[10:11], v[14:15], v[10:11]
	s_waitcnt lgkmcnt(0)
	v_mov_b32_e32 v5, v44
	v_mov_b32_e32 v7, v45
	v_mov_b32_e32 v9, v46
	v_mov_b32_e32 v11, v47
	v_pk_add_f32 v[4:5], v[4:5], v[6:7]
	v_pk_add_f32 v[6:7], v[8:9], v[10:11]
	s_lshl_b32 s72, s12, 4
	v_pk_add_f32 v[4:5], v[4:5], v[6:7]
	v_mov_b64_e32 v[6:7], s[88:89]
	v_pk_add_f32 v[4:5], v[4:5], v[4:5] op_sel:[0,1] op_sel_hi:[1,0]
	s_nop 0
	v_bfe_u32 v5, v4, 16, 1
	v_add3_u32 v8, v4, v5, s41
	v_lshl_add_u64 v[4:5], v[24:25], 0, s[94:95]
	v_mad_u64_u32 v[6:7], s[10:11], v4, s40, v[6:7]
	v_mad_i32_i24 v7, v5, s40, v7
	s_lshl_b32 s10, s13, 7
	s_mov_b32 s11, s73
	v_lshl_add_u64 v[4:5], v[6:7], 0, s[10:11]
	s_lshl_b32 s10, s12, 5
	v_lshl_add_u64 v[4:5], v[4:5], 0, s[10:11]
	s_lshl_b32 s10, s16, 4
	s_or_b32 s10, s10, s13
	s_ashr_i32 s11, s10, 31
	v_lshl_add_u64 v[4:5], v[4:5], 0, v[22:23]
	s_lshl_b64 s[10:11], s[10:11], 14
	global_store_short_d16_hi v[4:5], v8, off
	v_lshl_add_u64 v[4:5], s[72:73], 0, v[16:17]
	s_add_u32 s10, s34, s10
	v_lshlrev_b64 v[4:5], 8, v[4:5]
	s_addc_u32 s11, s35, s11
	v_lshl_add_u64 v[4:5], s[10:11], 0, v[4:5]
	v_lshlrev_b32_e32 v22, 2, v20
	v_lshl_add_u64 v[4:5], v[4:5], 0, v[22:23]
	global_store_dwordx4 v[4:5], v[0:3], off

.LBB0_1127:
	s_or_b64 exec, exec, s[10:11]
	v_lshlrev_b64 v[12:13], 1, v[48:49]
	v_lshlrev_b64 v[56:57], 1, v[50:51]
	v_lshl_add_u64 v[48:49], s[28:29], 0, v[12:13]
	v_lshl_add_u64 v[50:51], s[28:29], 0, v[56:57]
	v_lshl_add_u64 v[52:53], s[66:67], 0, v[12:13]
	v_lshl_add_u64 v[58:59], s[66:67], 0, v[56:57]
	global_load_dwordx2 v[88:89], v[48:49], off
	global_load_dwordx2 v[76:77], v[50:51], off
	global_load_dwordx2 v[86:87], v[52:53], off
	s_nop 0
	global_load_dwordx2 v[48:49], v[58:59], off
	v_lshl_add_u64 v[50:51], s[54:55], 0, v[12:13]
	v_lshl_add_u64 v[52:53], s[54:55], 0, v[56:57]
	v_lshl_add_u64 v[58:59], s[62:63], 0, v[12:13]
	v_lshl_add_u64 v[60:61], s[62:63], 0, v[56:57]
	v_lshl_add_u64 v[12:13], s[96:97], 0, v[12:13]
	v_lshl_add_u64 v[56:57], s[96:97], 0, v[56:57]
	v_lshlrev_b64 v[54:55], 1, v[54:55]
	v_lshlrev_b64 v[14:15], 1, v[14:15]
	global_load_dwordx2 v[80:81], v[50:51], off
	s_nop 0
	global_load_dwordx2 v[50:51], v[52:53], off
	global_load_dwordx2 v[78:79], v[58:59], off
	s_nop 0
	global_load_dwordx2 v[52:53], v[60:61], off
	v_lshl_add_u64 v[58:59], s[28:29], 0, v[54:55]
	v_lshl_add_u64 v[60:61], s[28:29], 0, v[14:15]
	global_load_dwordx2 v[82:83], v[12:13], off
	s_nop 0
	global_load_dwordx2 v[56:57], v[56:57], off
	s_nop 0
	global_load_dwordx2 v[96:97], v[58:59], off
	global_load_dwordx2 v[84:85], v[60:61], off
	v_lshl_add_u64 v[12:13], s[66:67], 0, v[54:55]
	v_lshl_add_u64 v[58:59], s[66:67], 0, v[14:15]
	v_lshl_add_u64 v[60:61], s[54:55], 0, v[54:55]
	v_lshl_add_u64 v[62:63], s[54:55], 0, v[14:15]
	global_load_dwordx2 v[98:99], v[12:13], off
	global_load_dwordx2 v[68:69], v[58:59], off
	global_load_dwordx2 v[90:91], v[60:61], off
	global_load_dwordx2 v[64:65], v[62:63], off
	v_lshl_add_u64 v[12:13], s[62:63], 0, v[54:55]
	v_lshl_add_u64 v[58:59], s[62:63], 0, v[14:15]
	v_lshl_add_u64 v[54:55], s[96:97], 0, v[54:55]
	v_lshl_add_u64 v[14:15], s[96:97], 0, v[14:15]
	global_load_dwordx2 v[92:93], v[12:13], off
	global_load_dwordx2 v[72:73], v[58:59], off
	global_load_dwordx2 v[94:95], v[54:55], off
	global_load_dwordx2 v[74:75], v[14:15], off
	s_lshr_b32 s8, s44, 2
	s_and_b32 s8, s8, 15
	s_and_b32 s9, s43, 3
	s_lshl_b32 s45, s8, 7
	s_lshl_b32 s47, s9, 5
	s_lshl_b32 s52, s8, 2
	s_lshl_b32 s8, s38, 1
	s_add_u32 s8, s88, s8
	s_addc_u32 s9, s89, 0
	s_lshl_b32 s10, s12, 5
	s_add_u32 s8, s8, s10
	s_addc_u32 s9, s9, 0
	s_lshl_b32 s10, s13, 2
	s_add_u32 s10, s58, s10
	v_lshlrev_b32_e32 v12, 1, v18
	v_mov_b32_e32 v13, v23
	s_addc_u32 s11, s59, 0
	s_lshl_b64 s[38:39], s[16:17], 23
	v_lshl_or_b32 v22, v20, 1, s45
	s_waitcnt lgkmcnt(0)
	s_barrier
	v_lshl_add_u64 v[54:55], s[8:9], 0, v[12:13]
	v_mov_b32_e32 v13, s39
	v_or_b32_e32 v12, s38, v32
	s_mul_hi_i32 s39, s16, 0x880000
	s_mul_i32 s38, s16, 0x880000
	s_or_b32 s45, s47, s45
	s_lshl_b64 s[16:17], s[16:17], 18
	s_or_b32 s38, s38, s45
	s_or_b32 s16, s16, s52
	v_cmp_eq_u32_e64 s[8:9], 0, v102
	v_cmp_eq_u32_e64 s[12:13], s12, v31
	v_lshl_add_u64 v[58:59], v[12:13], 0, v[22:23]
	v_lshl_add_u64 v[60:61], s[38:39], 0, v[34:35]
	v_lshl_add_u64 v[62:63], s[38:39], 0, v[38:39]
	v_lshl_add_u64 v[66:67], s[16:17], 0, v[40:41]
	s_mov_b32 s72, -1
	v_mov_b64_e32 v[70:71], v[36:37]
	s_mov_b64 s[98:99], exec
	s_andn2_b64 exec, exec, s[6:7]
	s_cbranch_execz .Lh1skipP
	s_waitcnt vmcnt(8)
	v_lshlrev_b32_e32 v13, 16, v52
	v_and_b32_e32 v15, 0xffff0000, v52
	v_lshlrev_b32_e32 v101, 16, v53
	s_waitcnt vmcnt(6)
	v_lshlrev_b32_e32 v100, 16, v49
	v_and_b32_e32 v103, 0xffff0000, v53
	v_and_b32_e32 v102, 0xffff0000, v49
	v_add_f32_e32 v117, -1.0, v102
	v_mov_b32_e32 v116, v103
	v_add_f32_e32 v113, -1.0, v100
	v_mov_b32_e32 v108, v13
	v_mov_b32_e32 v109, v15
	v_mov_b32_e32 v112, v101
	v_pk_mul_f32 v[114:115], v[44:45], v[116:117]
	v_pk_mul_f32 v[118:119], v[0:1], v[108:109]
	v_pk_mul_f32 v[120:121], v[46:47], v[112:113]
	v_pk_mul_f32 v[108:109], v[118:119], v[118:119]
	v_mov_b32_e32 v110, v114
	v_mov_b32_e32 v111, v120
	v_pk_mul_f32 v[110:111], v[110:111], v[110:111]
	v_add_f32_e32 v12, v108, v109
	v_add_f32_e32 v12, v12, v111
	v_add_f32_e32 v12, v110, v12
	s_waitcnt vmcnt(10)
	v_lshlrev_b32_e32 v106, 16, v56
	v_and_b32_e32 v107, 0xffff0000, v56
	v_add_f32_dpp v12, v12, v12 quad_perm:[1,0,3,2] row_mask:0xf bank_mask:0xf bound_ctrl:1
	v_lshlrev_b32_e32 v104, 16, v57
	v_and_b32_e32 v105, 0xffff0000, v57
	v_add_f32_dpp v12, v12, v12 quad_perm:[2,3,0,1] row_mask:0xf bank_mask:0xf bound_ctrl:1
	s_nop 1
	v_add_f32_dpp v12, v12, v12 row_ror:4 row_mask:0xf bank_mask:0xf bound_ctrl:1
	s_nop 1
	v_add_f32_dpp v12, v12, v12 row_ror:8 row_mask:0xf bank_mask:0xf bound_ctrl:1
	v_mul_f32_e32 v14, 0x4f800000, v12
	v_cmp_gt_f32_e32 vcc, s42, v12
	s_nop 1
	v_cndmask_b32_e32 v22, v12, v14, vcc
	v_sqrt_f32_e32 v42, v22
	v_lshlrev_b32_e32 v12, 16, v48
	v_and_b32_e32 v14, 0xffff0000, v48
	v_add_f32_e32 v108, -1.0, v12
	v_add_u32_e32 v109, -1, v42
	v_fma_f32 v110, -v109, v42, v22
	v_cmp_ge_f32_e64 s[16:17], 0, v110
	v_add_u32_e32 v110, 1, v42
	s_nop 0
	v_cndmask_b32_e64 v109, v42, v109, s[16:17]
	v_fma_f32 v42, -v110, v42, v22
	v_cmp_lt_f32_e64 s[16:17], 0, v42
	s_nop 1
	v_cndmask_b32_e64 v42, v109, v110, s[16:17]
	v_mul_f32_e32 v109, 0x37800000, v42
	v_cndmask_b32_e32 v42, v42, v109, vcc
	v_cmp_class_f32_e32 vcc, v22, v149
	v_fma_f32 v109, v4, v108, 1.0
	v_add_f32_e32 v108, -1.0, v14
	v_cndmask_b32_e32 v22, v42, v22, vcc
	v_max_f32_e32 v22, 0x2b8cbccc, v22
	v_div_scale_f32 v42, s[16:17], v22, v22, 1.0
	v_rcp_f32_e32 v110, v42
	v_fma_f32 v111, v5, v108, 1.0
	v_fma_f32 v108, -v42, v110, 1.0
	v_fmac_f32_e32 v110, v108, v110
	v_div_scale_f32 v108, vcc, 1.0, v22, 1.0
	v_mul_f32_e32 v122, v108, v110
	v_fma_f32 v123, -v42, v122, v108
	v_fmac_f32_e32 v122, v123, v110
	v_fma_f32 v42, -v42, v122, v108
	v_div_fmas_f32 v42, v42, v110, v122
	v_div_fixup_f32 v42, v42, v22, 1.0
	v_mul_f32_e32 v108, v118, v42
	v_mul_f32_e32 v110, v119, v42
	v_pk_mul_f32 v[108:109], v[108:109], v[12:13]
	v_pk_mul_f32 v[110:111], v[110:111], v[14:15]
	v_pk_mul_f32 v[12:13], v[120:121], v[42:43]
	v_pk_fma_f32 v[14:15], v[46:47], v[112:113], s[2:3]
	v_pk_mul_f32 v[122:123], v[108:109], v[106:107] op_sel:[1,0] op_sel_hi:[0,1]
	v_mov_b32_e32 v13, v15
	v_pk_mul_f32 v[112:113], v[12:13], v[100:101]
	v_pk_mul_f32 v[12:13], v[114:115], v[42:43]
	v_pk_fma_f32 v[14:15], v[44:45], v[116:117], s[2:3]
	v_fma_f32 v22, v8, v122, 0
	v_pk_mul_f32 v[124:125], v[110:111], v[106:107]
	v_mov_b32_e32 v13, v15
	v_fmac_f32_e32 v22, v9, v125
	v_pk_mul_f32 v[130:131], v[112:113], v[104:105] op_sel:[1,0] op_sel_hi:[0,1]
	v_pk_mul_f32 v[116:117], v[12:13], v[102:103]
	v_fmac_f32_e32 v22, v10, v130
	v_pk_mul_f32 v[132:133], v[116:117], v[104:105]
	s_nop 0
	v_fmac_f32_e32 v22, v11, v133
	s_nop 1
	v_add_f32_dpp v12, v22, v22 quad_perm:[1,0,3,2] row_mask:0xf bank_mask:0xf bound_ctrl:1
	s_nop 1
	v_add_f32_dpp v12, v12, v12 quad_perm:[2,3,0,1] row_mask:0xf bank_mask:0xf bound_ctrl:1
	s_nop 1
	v_add_f32_dpp v12, v12, v12 row_ror:4 row_mask:0xf bank_mask:0xf bound_ctrl:1
	s_nop 1
.Lh1skipP:
	s_mov_b64 exec, s[98:99]
	s_branch .LBB0_1129
.LBB0_1128:
	s_or_b64 exec, exec, s[38:39]
	s_mov_b64 s[98:99], exec
	s_andn2_b64 exec, exec, s[6:7]
	s_cbranch_execz .Lh1skip0
	s_waitcnt vmcnt(8)
	v_lshlrev_b32_e32 v13, 16, v52
	v_and_b32_e32 v15, 0xffff0000, v52
	v_lshlrev_b32_e32 v101, 16, v53
	s_waitcnt vmcnt(6)
	v_lshlrev_b32_e32 v100, 16, v49
	v_and_b32_e32 v103, 0xffff0000, v53
	v_and_b32_e32 v102, 0xffff0000, v49
	v_add_f32_e32 v117, -1.0, v102
	v_mov_b32_e32 v116, v103
	v_add_f32_e32 v113, -1.0, v100
	v_mov_b32_e32 v108, v13
	v_mov_b32_e32 v109, v15
	v_mov_b32_e32 v112, v101
	v_pk_mul_f32 v[114:115], v[44:45], v[116:117]
	v_pk_mul_f32 v[118:119], v[0:1], v[108:109]
	v_pk_mul_f32 v[120:121], v[46:47], v[112:113]
	v_pk_mul_f32 v[108:109], v[118:119], v[118:119]
	v_mov_b32_e32 v110, v114
	v_mov_b32_e32 v111, v120
	v_pk_mul_f32 v[110:111], v[110:111], v[110:111]
	v_add_f32_e32 v12, v108, v109
	v_add_f32_e32 v12, v12, v111
	v_add_f32_e32 v12, v110, v12
	s_waitcnt vmcnt(10)
	v_lshlrev_b32_e32 v106, 16, v56
	v_and_b32_e32 v107, 0xffff0000, v56
	v_add_f32_dpp v12, v12, v12 quad_perm:[1,0,3,2] row_mask:0xf bank_mask:0xf bound_ctrl:1
	v_lshlrev_b32_e32 v104, 16, v57
	v_and_b32_e32 v105, 0xffff0000, v57
	v_add_f32_dpp v12, v12, v12 quad_perm:[2,3,0,1] row_mask:0xf bank_mask:0xf bound_ctrl:1
	s_nop 1
	v_add_f32_dpp v12, v12, v12 row_ror:4 row_mask:0xf bank_mask:0xf bound_ctrl:1
	s_nop 1
	v_add_f32_dpp v12, v12, v12 row_ror:8 row_mask:0xf bank_mask:0xf bound_ctrl:1
	v_mul_f32_e32 v14, 0x4f800000, v12
	v_cmp_gt_f32_e32 vcc, s42, v12
	s_nop 1
	v_cndmask_b32_e32 v22, v12, v14, vcc
	v_sqrt_f32_e32 v42, v22
	v_lshlrev_b32_e32 v12, 16, v48
	v_and_b32_e32 v14, 0xffff0000, v48
	v_add_f32_e32 v108, -1.0, v12
	v_add_u32_e32 v109, -1, v42
	v_fma_f32 v110, -v109, v42, v22
	v_cmp_ge_f32_e64 s[16:17], 0, v110
	v_add_u32_e32 v110, 1, v42
	s_nop 0
	v_cndmask_b32_e64 v109, v42, v109, s[16:17]
	v_fma_f32 v42, -v110, v42, v22
	v_cmp_lt_f32_e64 s[16:17], 0, v42
	s_nop 1
	v_cndmask_b32_e64 v42, v109, v110, s[16:17]
	v_mul_f32_e32 v109, 0x37800000, v42
	v_cndmask_b32_e32 v42, v42, v109, vcc
	v_cmp_class_f32_e32 vcc, v22, v149
	v_fma_f32 v109, v4, v108, 1.0
	v_add_f32_e32 v108, -1.0, v14
	v_cndmask_b32_e32 v22, v42, v22, vcc
	v_max_f32_e32 v22, 0x2b8cbccc, v22
	v_div_scale_f32 v42, s[16:17], v22, v22, 1.0
	v_rcp_f32_e32 v110, v42
	v_fma_f32 v111, v5, v108, 1.0
	v_fma_f32 v108, -v42, v110, 1.0
	v_fmac_f32_e32 v110, v108, v110
	v_div_scale_f32 v108, vcc, 1.0, v22, 1.0
	v_mul_f32_e32 v122, v108, v110
	v_fma_f32 v123, -v42, v122, v108
	v_fmac_f32_e32 v122, v123, v110
	v_fma_f32 v42, -v42, v122, v108
	v_div_fmas_f32 v42, v42, v110, v122
	v_div_fixup_f32 v42, v42, v22, 1.0
	v_mul_f32_e32 v108, v118, v42
	v_mul_f32_e32 v110, v119, v42
	v_pk_mul_f32 v[108:109], v[108:109], v[12:13]
	v_pk_mul_f32 v[110:111], v[110:111], v[14:15]
	v_pk_mul_f32 v[12:13], v[120:121], v[42:43]
	v_pk_fma_f32 v[14:15], v[46:47], v[112:113], s[2:3]
	v_pk_mul_f32 v[122:123], v[108:109], v[106:107] op_sel:[1,0] op_sel_hi:[0,1]
	v_mov_b32_e32 v13, v15
	v_pk_mul_f32 v[112:113], v[12:13], v[100:101]
	v_pk_mul_f32 v[12:13], v[114:115], v[42:43]
	v_pk_fma_f32 v[14:15], v[44:45], v[116:117], s[2:3]
	v_fma_f32 v22, v8, v122, 0
	v_pk_mul_f32 v[124:125], v[110:111], v[106:107]
	v_mov_b32_e32 v13, v15
	v_fmac_f32_e32 v22, v9, v125
	v_pk_mul_f32 v[130:131], v[112:113], v[104:105] op_sel:[1,0] op_sel_hi:[0,1]
	v_pk_mul_f32 v[116:117], v[12:13], v[102:103]
	v_fmac_f32_e32 v22, v10, v130
	v_pk_mul_f32 v[132:133], v[116:117], v[104:105]
	s_nop 0
	v_fmac_f32_e32 v22, v11, v133
	s_nop 1
	v_add_f32_dpp v12, v22, v22 quad_perm:[1,0,3,2] row_mask:0xf bank_mask:0xf bound_ctrl:1
	s_nop 1
	v_add_f32_dpp v12, v12, v12 quad_perm:[2,3,0,1] row_mask:0xf bank_mask:0xf bound_ctrl:1
	s_nop 1
	v_add_f32_dpp v12, v12, v12 row_ror:4 row_mask:0xf bank_mask:0xf bound_ctrl:1
	s_nop 1
.Lh1skip0:
	s_mov_b64 exec, s[98:99]
	s_waitcnt lgkmcnt(0)
	s_barrier
	s_mov_b64 s[16:17], 0x20000
	s_add_i32 s72, s72, 4
	v_lshl_add_u64 v[58:59], v[58:59], 0, s[16:17]
	s_mov_b64 s[16:17], 0x1000
	v_lshl_add_u64 v[60:61], v[60:61], 0, s[90:91]
	v_lshl_add_u64 v[70:71], v[70:71], 0, 64
	v_lshl_add_u64 v[62:63], v[62:63], 0, s[90:91]
	s_cmpk_gt_u32 s45, 0xfb
	v_lshl_add_u64 v[66:67], v[66:67], 0, s[16:17]
	s_cbranch_scc1 .LBB0_1109

.LBB0_1132:
	s_or_saveexec_b64 s[38:39], s[16:17]
	s_add_i32 s45, s72, 1
	s_xor_b64 exec, exec, s[38:39]
	s_cbranch_execz .LBB0_1141
	v_mov_b32_dpp v13, v12 row_ror:8 row_mask:0xf bank_mask:0xf bound_ctrl:1
	s_and_saveexec_b64 s[16:17], s[8:9]
	s_cbranch_execz .LBB0_1135
	v_lshl_add_u64 v[14:15], s[84:85], 0, v[66:67]
	v_add_f32_e32 v12, v12, v13
	global_store_dword v[14:15], v12, off offset:-2048

.LBB0_1163:
	s_or_b64 exec, exec, s[38:39]
	s_mov_b64 s[98:99], exec
	s_andn2_b64 exec, exec, s[14:15]
	s_cbranch_execz .Lh1skip3
	s_waitcnt vmcnt(8)
	v_lshlrev_b32_e32 v13, 16, v52
	v_and_b32_e32 v15, 0xffff0000, v52
	v_lshlrev_b32_e32 v101, 16, v53
	s_waitcnt vmcnt(6)
	v_lshlrev_b32_e32 v100, 16, v49
	v_and_b32_e32 v103, 0xffff0000, v53
	v_and_b32_e32 v102, 0xffff0000, v49
	v_add_f32_e32 v117, -1.0, v102
	v_mov_b32_e32 v116, v103
	v_add_f32_e32 v113, -1.0, v100
	v_mov_b32_e32 v108, v13
	v_mov_b32_e32 v109, v15
	v_mov_b32_e32 v112, v101
	v_pk_mul_f32 v[114:115], v[44:45], v[116:117]
	v_pk_mul_f32 v[118:119], v[0:1], v[108:109]
	v_pk_mul_f32 v[120:121], v[46:47], v[112:113]
	v_pk_mul_f32 v[108:109], v[118:119], v[118:119]
	v_mov_b32_e32 v110, v114
	v_mov_b32_e32 v111, v120
	v_pk_mul_f32 v[110:111], v[110:111], v[110:111]
	v_add_f32_e32 v12, v108, v109
	v_add_f32_e32 v12, v12, v111
	v_add_f32_e32 v12, v110, v12
	v_lshlrev_b32_e32 v106, 16, v56
	v_and_b32_e32 v107, 0xffff0000, v56
	v_add_f32_dpp v12, v12, v12 quad_perm:[1,0,3,2] row_mask:0xf bank_mask:0xf bound_ctrl:1
	v_lshlrev_b32_e32 v104, 16, v57
	v_and_b32_e32 v105, 0xffff0000, v57
	v_add_f32_dpp v12, v12, v12 quad_perm:[2,3,0,1] row_mask:0xf bank_mask:0xf bound_ctrl:1
	v_lshl_add_u64 v[142:143], s[84:85], 0, v[66:67]
	s_nop 0
	v_add_f32_dpp v12, v12, v12 row_ror:4 row_mask:0xf bank_mask:0xf bound_ctrl:1
	s_nop 1
	v_add_f32_dpp v12, v12, v12 row_ror:8 row_mask:0xf bank_mask:0xf bound_ctrl:1
	v_mul_f32_e32 v14, 0x4f800000, v12
	v_cmp_gt_f32_e32 vcc, s42, v12
	s_nop 1
	v_cndmask_b32_e32 v22, v12, v14, vcc
	v_sqrt_f32_e32 v42, v22
	v_lshlrev_b32_e32 v12, 16, v48
	v_and_b32_e32 v14, 0xffff0000, v48
	v_add_f32_e32 v108, -1.0, v12
	v_add_u32_e32 v109, -1, v42
	v_fma_f32 v110, -v109, v42, v22
	v_cmp_ge_f32_e64 s[16:17], 0, v110
	v_add_u32_e32 v110, 1, v42
	s_nop 0
	v_cndmask_b32_e64 v109, v42, v109, s[16:17]
	v_fma_f32 v42, -v110, v42, v22
	v_cmp_lt_f32_e64 s[16:17], 0, v42
	s_nop 1
	v_cndmask_b32_e64 v42, v109, v110, s[16:17]
	v_mul_f32_e32 v109, 0x37800000, v42
	v_cndmask_b32_e32 v42, v42, v109, vcc
	v_cmp_class_f32_e32 vcc, v22, v149
	v_fma_f32 v109, v4, v108, 1.0
	v_add_f32_e32 v108, -1.0, v14
	v_cndmask_b32_e32 v22, v42, v22, vcc
	v_max_f32_e32 v22, 0x2b8cbccc, v22
	v_div_scale_f32 v42, s[16:17], v22, v22, 1.0
	v_rcp_f32_e32 v110, v42
	v_fma_f32 v111, v5, v108, 1.0
	v_fma_f32 v108, -v42, v110, 1.0
	v_fmac_f32_e32 v110, v108, v110
	v_div_scale_f32 v108, vcc, 1.0, v22, 1.0
	v_mul_f32_e32 v122, v108, v110
	v_fma_f32 v123, -v42, v122, v108
	v_fmac_f32_e32 v122, v123, v110
	v_fma_f32 v42, -v42, v122, v108
	v_div_fmas_f32 v42, v42, v110, v122
	v_div_fixup_f32 v42, v42, v22, 1.0
	v_mul_f32_e32 v108, v118, v42
	v_mul_f32_e32 v110, v119, v42
	v_pk_mul_f32 v[108:109], v[108:109], v[12:13]
	v_pk_mul_f32 v[110:111], v[110:111], v[14:15]
	v_pk_mul_f32 v[12:13], v[120:121], v[42:43]
	v_pk_fma_f32 v[14:15], v[46:47], v[112:113], s[2:3]
	v_pk_mul_f32 v[122:123], v[108:109], v[106:107] op_sel:[1,0] op_sel_hi:[0,1]
	v_mov_b32_e32 v13, v15
	v_pk_mul_f32 v[112:113], v[12:13], v[100:101]
	v_pk_mul_f32 v[12:13], v[114:115], v[42:43]
	v_pk_fma_f32 v[14:15], v[44:45], v[116:117], s[2:3]
	v_fma_f32 v22, v8, v122, 0
	v_pk_mul_f32 v[124:125], v[110:111], v[106:107]
	v_mov_b32_e32 v13, v15
	v_fmac_f32_e32 v22, v9, v125
	v_pk_mul_f32 v[130:131], v[112:113], v[104:105] op_sel:[1,0] op_sel_hi:[0,1]
	v_pk_mul_f32 v[116:117], v[12:13], v[102:103]
	v_fmac_f32_e32 v22, v10, v130
	v_pk_mul_f32 v[132:133], v[116:117], v[104:105]
	s_nop 0
	v_fmac_f32_e32 v22, v11, v133
	s_nop 1
	v_add_f32_dpp v12, v22, v22 quad_perm:[1,0,3,2] row_mask:0xf bank_mask:0xf bound_ctrl:1
	s_nop 1
	v_add_f32_dpp v12, v12, v12 quad_perm:[2,3,0,1] row_mask:0xf bank_mask:0xf bound_ctrl:1
	s_nop 1
	v_add_f32_dpp v12, v12, v12 row_ror:4 row_mask:0xf bank_mask:0xf bound_ctrl:1
	s_nop 1
.Lh1skip3:
	s_mov_b64 exec, s[98:99]
	s_waitcnt lgkmcnt(0)
	s_barrier
	s_and_saveexec_b64 s[16:17], s[14:15]
	s_xor_b64 s[16:17], exec, s[16:17]
	s_cbranch_execz .LBB0_1165
	ds_read_b128 v[12:15], v146 offset:39936
	ds_read_b128 v[104:107], v146 offset:39952
	ds_read_b128 v[108:111], v146 offset:39968
	ds_read_b128 v[112:115], v146 offset:39984
	s_mov_b32 s38, 0x3029000
	s_waitcnt lgkmcnt(3)
	v_add_f32_e32 v12, v12, v13
	v_add_f32_e32 v13, v14, v15
	v_add_f32_e32 v12, v12, v13
	s_waitcnt lgkmcnt(2)
	v_add_f32_e32 v13, v104, v105
	v_add_f32_e32 v14, v106, v107
	v_add_f32_e32 v13, v13, v14
	v_add_f32_e32 v12, v12, v13
	s_waitcnt lgkmcnt(1)
	v_add_f32_e32 v13, v108, v109
	v_add_f32_e32 v14, v110, v111
	v_add_f32_e32 v13, v13, v14
	v_add_f32_e32 v12, v12, v13
	s_waitcnt lgkmcnt(0)
	v_add_f32_e32 v13, v112, v113
	v_add_f32_e32 v14, v114, v115
	v_add_f32_e32 v13, v13, v14
	v_add_f32_e32 v12, v12, v13
	v_bfe_u32 v13, v12, 16, 1
	v_add3_u32 v22, v12, v13, s41
	v_add_co_u32_e32 v102, vcc, s38, v102
	ds_read_b128 v[12:15], v147 offset:39936
	s_nop 0
	v_addc_co_u32_e32 v103, vcc, 0, v103, vcc
	global_store_short_d16_hi v[102:103], v22, off
	ds_read_b128 v[102:105], v147 offset:39952
	ds_read_b128 v[106:109], v147 offset:39968
	ds_read_b128 v[110:113], v147 offset:39984
	s_waitcnt lgkmcnt(3)
	v_add_f32_e32 v12, v12, v13
	v_add_f32_e32 v13, v14, v15
	v_add_f32_e32 v12, v12, v13
	s_waitcnt lgkmcnt(2)
	v_add_f32_e32 v13, v102, v103
	v_add_f32_e32 v14, v104, v105
	v_add_f32_e32 v13, v13, v14
	v_add_f32_e32 v12, v12, v13
	s_waitcnt lgkmcnt(1)
	v_add_f32_e32 v13, v106, v107
	v_add_f32_e32 v14, v108, v109
	v_add_f32_e32 v13, v13, v14
	v_add_f32_e32 v12, v12, v13
	s_waitcnt lgkmcnt(0)
	v_add_f32_e32 v13, v110, v111
	v_add_f32_e32 v14, v112, v113
	v_add_f32_e32 v13, v13, v14
	v_add_f32_e32 v12, v12, v13
	v_bfe_u32 v13, v12, 16, 1
	v_add3_u32 v14, v12, v13, s41
	v_add_co_u32_e32 v12, vcc, 0x3029000, v100
	s_nop 1
	v_addc_co_u32_e32 v13, vcc, 0, v101, vcc
	global_store_short_d16_hi v[12:13], v14, off
.LBB0_1165:
	s_andn2_saveexec_b64 s[38:39], s[16:17]
	s_cbranch_execz .LBB0_1128
	s_cmpk_gt_u32 s45, 0xfb
	s_cbranch_scc1 .LBB0_1176
	v_mov_b32_dpp v13, v12 row_ror:8 row_mask:0xf bank_mask:0xf bound_ctrl:1
	s_and_saveexec_b64 s[16:17], s[8:9]
	s_cbranch_execz .LBB0_1169
	v_add_f32_e32 v12, v12, v13
	global_store_dword v[142:143], v12, off offset:1024

.Lqv_orig:
	s_cmp_lt_u32 s62, 0x4000
	s_cbranch_scc0 .Lqk_orig
	s_cmpk_le_i32 s4, 0x400
	s_cbranch_scc0 .Lqk_orig
	v_lshlrev_b32_e32 v248, 2, v130
	global_load_dwordx4 v[194:197], v248, s[68:69] offset:0
	global_load_dwordx4 v[198:201], v248, s[68:69] offset:64
	global_load_dwordx4 v[202:205], v248, s[68:69] offset:128
	global_load_dwordx4 v[206:209], v248, s[68:69] offset:192
	s_and_b32 s0, s62, 0xfff
	s_lshl_b32 s1, s5, 7
	s_add_i32 s0, s0, s1
	v_add_u32_e32 v247, s0, v176
	v_lshlrev_b32_e32 v247, 6, v247
	v_and_b32_e32 v248, 1, v172
	v_lshl_add_u32 v247, v248, 5, v247
	global_load_dwordx4 v[210:213], v247, s[16:17]
	global_load_dwordx4 v[214:217], v247, s[16:17] offset:16
	v_add_u32_e32 v247, 0x400, v247
	global_load_dwordx4 v[218:221], v247, s[16:17]
	global_load_dwordx4 v[222:225], v247, s[16:17] offset:16
	v_add_u32_e32 v247, 0x400, v247
	v_cmp_gt_u32_e64 s[12:13], 32, v173
	s_cmpk_eq_i32 s4, 0x400
	s_cselect_b32 s9, 9, 11
	s_cselect_b32 s1, 0x400, 0
	s_cselect_b32 s7, 1, 0
	s_mov_b32 s10, 0x5a188c0
	s_cselect_b32 s10, 0x9d208c0, s10
	s_add_u32 s10, s84, s10
	s_addc_u32 s11, s85, 0
	v_add_u32_e32 v248, s62, v176
	s_lshl_b32 s0, s5, 7
	v_add_u32_e32 v248, s0, v248
	v_mov_b32_e32 v249, 0
	v_lshlrev_b64 v[234:235], s9, v[248:249]
	v_lshl_add_u64 v[234:235], s[10:11], 0, v[234:235]
	v_subrev_u32_e32 v248, s1, v130
	v_lshlrev_b32_e32 v248, 1, v248
	v_and_b32_e32 v250, 1, v172
	v_mul_u32_u24_e32 v250, 24, v250
	v_add_u32_e32 v248, v248, v250
	v_lshl_add_u64 v[234:235], v[234:235], 0, v[248:249]
	s_lshl_b32 s0, 16, s9
	v_mov_b32_e32 v236, s0
	v_mov_b32_e32 v237, 0
	s_and_b32 s0, s62, 0xf00
	s_cmpk_eq_i32 s0, 0xf00
	s_cselect_b32 s0, 1, 0
	s_and_b32 s7, s7, s0
	s_and_b32 s7, s7, s5
	s_lshr_b32 s0, s62, 12
	s_lshl_b32 s0, s0, 7
	v_add_u32_e32 v246, s0, v176
	v_lshlrev_b32_e32 v246, 10, v246
	s_lshl_b32 s0, s6, 8
	s_add_u32 s0, s0, 0x6204000
	v_lshl_add_u32 v246, v172, 4, v246
	v_add_u32_e32 v246, s0, v246
	s_waitcnt vmcnt(4)
	v_add_f32_e32 v126, v126, v194
	v_add_f32_e32 v127, v127, v195
	v_add_f32_e32 v128, v128, v196
	v_add_f32_e32 v129, v129, v197
	v_add_f32_e32 v122, v122, v198
	v_add_f32_e32 v123, v123, v199
	v_add_f32_e32 v124, v124, v200
	v_add_f32_e32 v125, v125, v201
	v_add_f32_e32 v118, v118, v202
	v_add_f32_e32 v119, v119, v203
	v_add_f32_e32 v120, v120, v204
	v_add_f32_e32 v121, v121, v205
	v_add_f32_e32 v114, v114, v206
	v_add_f32_e32 v115, v115, v207
	v_add_f32_e32 v116, v116, v208
	v_add_f32_e32 v117, v117, v209
	v_mov_b32_e32 v238, v126
	v_mov_b32_e32 v239, v127
	v_mov_b32_e32 v240, v128
	v_mov_b32_e32 v241, v129
	v_permlane32_swap_b32_e32 v238, v126
	v_permlane32_swap_b32_e32 v239, v127
	v_permlane32_swap_b32_e32 v240, v128
	v_permlane32_swap_b32_e32 v241, v129
	s_waitcnt vmcnt(2)
	v_cndmask_b32_e64 v242, v238, -v126, s[12:13]
	v_cndmask_b32_e64 v238, v126, v238, s[12:13]
	v_cndmask_b32_e64 v243, v239, -v127, s[12:13]
	v_cndmask_b32_e64 v239, v127, v239, s[12:13]
	v_cndmask_b32_e64 v244, v240, -v128, s[12:13]
	v_cndmask_b32_e64 v240, v128, v240, s[12:13]
	v_cndmask_b32_e64 v245, v241, -v129, s[12:13]
	v_cndmask_b32_e64 v241, v129, v241, s[12:13]
	v_mul_f32_e32 v242, v242, v211
	v_mul_f32_e32 v243, v243, v213
	v_mul_f32_e32 v244, v244, v215
	v_mul_f32_e32 v245, v245, v217
	v_fma_f32 v126, v238, v210, v242
	v_fma_f32 v127, v239, v212, v243
	v_fma_f32 v128, v240, v214, v244
	v_fma_f32 v129, v241, v216, v245
	s_cmp_lg_u32 s7, 0
	s_cbranch_scc0 .Lqk_nc0
	global_store_dwordx4 v246, v[126:129], s[82:83] offset:0
	global_store_dwordx4 v246, v[122:125], s[82:83] offset:64
	global_store_dwordx4 v246, v[118:121], s[82:83] offset:128
	global_store_dwordx4 v246, v[114:117], s[82:83] offset:192
	v_add_u32_e32 v246, 0x4000, v246
.Lqk_nc0:
	v_cvt_pk_bf16_f32 v226, v126, v127
	v_cvt_pk_bf16_f32 v227, v128, v129
	v_cvt_pk_bf16_f32 v228, v122, v123
	v_cvt_pk_bf16_f32 v229, v124, v125
	v_cvt_pk_bf16_f32 v230, v118, v119
	v_cvt_pk_bf16_f32 v231, v120, v121
	v_cvt_pk_bf16_f32 v232, v114, v115
	v_cvt_pk_bf16_f32 v233, v116, v117
	s_nop 1
	v_permlane16_swap_b32_e32 v226, v228
	v_permlane16_swap_b32_e32 v227, v229
	v_permlane16_swap_b32_e32 v230, v232
	v_permlane16_swap_b32_e32 v231, v233
	global_store_dwordx4 v[234:235], v[226:229], off
	global_store_dwordx4 v[234:235], v[230:233], off offset:64
	v_lshl_add_u64 v[234:235], v[234:235], 0, v[236:237]
	global_load_dwordx4 v[210:213], v247, s[16:17]
	global_load_dwordx4 v[214:217], v247, s[16:17] offset:16
	v_add_u32_e32 v247, 0x400, v247
	v_add_f32_e32 v110, v110, v194
	v_add_f32_e32 v111, v111, v195
	v_add_f32_e32 v112, v112, v196
	v_add_f32_e32 v113, v113, v197
	v_add_f32_e32 v106, v106, v198
	v_add_f32_e32 v107, v107, v199
	v_add_f32_e32 v108, v108, v200
	v_add_f32_e32 v109, v109, v201
	v_add_f32_e32 v102, v102, v202
	v_add_f32_e32 v103, v103, v203
	v_add_f32_e32 v104, v104, v204
	v_add_f32_e32 v105, v105, v205
	v_add_f32_e32 v98, v98, v206
	v_add_f32_e32 v99, v99, v207
	v_add_f32_e32 v100, v100, v208
	v_add_f32_e32 v101, v101, v209
	v_mov_b32_e32 v238, v110
	v_mov_b32_e32 v239, v111
	v_mov_b32_e32 v240, v112
	v_mov_b32_e32 v241, v113
	v_permlane32_swap_b32_e32 v238, v110
	v_permlane32_swap_b32_e32 v239, v111
	v_permlane32_swap_b32_e32 v240, v112
	v_permlane32_swap_b32_e32 v241, v113
	s_waitcnt vmcnt(4)
	v_cndmask_b32_e64 v242, v238, -v110, s[12:13]
	v_cndmask_b32_e64 v238, v110, v238, s[12:13]
	v_cndmask_b32_e64 v243, v239, -v111, s[12:13]
	v_cndmask_b32_e64 v239, v111, v239, s[12:13]
	v_cndmask_b32_e64 v244, v240, -v112, s[12:13]
	v_cndmask_b32_e64 v240, v112, v240, s[12:13]
	v_cndmask_b32_e64 v245, v241, -v113, s[12:13]
	v_cndmask_b32_e64 v241, v113, v241, s[12:13]
	v_mul_f32_e32 v242, v242, v219
	v_mul_f32_e32 v243, v243, v221
	v_mul_f32_e32 v244, v244, v223
	v_mul_f32_e32 v245, v245, v225
	v_fma_f32 v110, v238, v218, v242
	v_fma_f32 v111, v239, v220, v243
	v_fma_f32 v112, v240, v222, v244
	v_fma_f32 v113, v241, v224, v245
	s_cmp_lg_u32 s7, 0
	s_cbranch_scc0 .Lqk_nc1
	global_store_dwordx4 v246, v[110:113], s[82:83] offset:0
	global_store_dwordx4 v246, v[106:109], s[82:83] offset:64
	global_store_dwordx4 v246, v[102:105], s[82:83] offset:128
	global_store_dwordx4 v246, v[98:101], s[82:83] offset:192
	v_add_u32_e32 v246, 0x4000, v246
.Lqk_nc1:
	v_cvt_pk_bf16_f32 v226, v110, v111
	v_cvt_pk_bf16_f32 v227, v112, v113
	v_cvt_pk_bf16_f32 v228, v106, v107
	v_cvt_pk_bf16_f32 v229, v108, v109
	v_cvt_pk_bf16_f32 v230, v102, v103
	v_cvt_pk_bf16_f32 v231, v104, v105
	v_cvt_pk_bf16_f32 v232, v98, v99
	v_cvt_pk_bf16_f32 v233, v100, v101
	s_nop 1
	v_permlane16_swap_b32_e32 v226, v228
	v_permlane16_swap_b32_e32 v227, v229
	v_permlane16_swap_b32_e32 v230, v232
	v_permlane16_swap_b32_e32 v231, v233
	global_store_dwordx4 v[234:235], v[226:229], off
	global_store_dwordx4 v[234:235], v[230:233], off offset:64
	v_lshl_add_u64 v[234:235], v[234:235], 0, v[236:237]
	global_load_dwordx4 v[218:221], v247, s[16:17]
	global_load_dwordx4 v[222:225], v247, s[16:17] offset:16
	v_add_u32_e32 v247, 0x400, v247
	v_add_f32_e32 v94, v94, v194
	v_add_f32_e32 v95, v95, v195
	v_add_f32_e32 v96, v96, v196
	v_add_f32_e32 v97, v97, v197
	v_add_f32_e32 v90, v90, v198
	v_add_f32_e32 v91, v91, v199
	v_add_f32_e32 v92, v92, v200
	v_add_f32_e32 v93, v93, v201
	v_add_f32_e32 v86, v86, v202
	v_add_f32_e32 v87, v87, v203
	v_add_f32_e32 v88, v88, v204
	v_add_f32_e32 v89, v89, v205
	v_add_f32_e32 v82, v82, v206
	v_add_f32_e32 v83, v83, v207
	v_add_f32_e32 v84, v84, v208
	v_add_f32_e32 v85, v85, v209
	v_mov_b32_e32 v238, v94
	v_mov_b32_e32 v239, v95
	v_mov_b32_e32 v240, v96
	v_mov_b32_e32 v241, v97
	v_permlane32_swap_b32_e32 v238, v94
	v_permlane32_swap_b32_e32 v239, v95
	v_permlane32_swap_b32_e32 v240, v96
	v_permlane32_swap_b32_e32 v241, v97
	s_waitcnt vmcnt(4)
	v_cndmask_b32_e64 v242, v238, -v94, s[12:13]
	v_cndmask_b32_e64 v238, v94, v238, s[12:13]
	v_cndmask_b32_e64 v243, v239, -v95, s[12:13]
	v_cndmask_b32_e64 v239, v95, v239, s[12:13]
	v_cndmask_b32_e64 v244, v240, -v96, s[12:13]
	v_cndmask_b32_e64 v240, v96, v240, s[12:13]
	v_cndmask_b32_e64 v245, v241, -v97, s[12:13]
	v_cndmask_b32_e64 v241, v97, v241, s[12:13]
	v_mul_f32_e32 v242, v242, v211
	v_mul_f32_e32 v243, v243, v213
	v_mul_f32_e32 v244, v244, v215
	v_mul_f32_e32 v245, v245, v217
	v_fma_f32 v94, v238, v210, v242
	v_fma_f32 v95, v239, v212, v243
	v_fma_f32 v96, v240, v214, v244
	v_fma_f32 v97, v241, v216, v245
	s_cmp_lg_u32 s7, 0
	s_cbranch_scc0 .Lqk_nc2
	global_store_dwordx4 v246, v[94:97], s[82:83] offset:0
	global_store_dwordx4 v246, v[90:93], s[82:83] offset:64
	global_store_dwordx4 v246, v[86:89], s[82:83] offset:128
	global_store_dwordx4 v246, v[82:85], s[82:83] offset:192
	v_add_u32_e32 v246, 0x4000, v246
.Lqk_nc2:
	v_cvt_pk_bf16_f32 v226, v94, v95
	v_cvt_pk_bf16_f32 v227, v96, v97
	v_cvt_pk_bf16_f32 v228, v90, v91
	v_cvt_pk_bf16_f32 v229, v92, v93
	v_cvt_pk_bf16_f32 v230, v86, v87
	v_cvt_pk_bf16_f32 v231, v88, v89
	v_cvt_pk_bf16_f32 v232, v82, v83
	v_cvt_pk_bf16_f32 v233, v84, v85
	s_nop 1
	v_permlane16_swap_b32_e32 v226, v228
	v_permlane16_swap_b32_e32 v227, v229
	v_permlane16_swap_b32_e32 v230, v232
	v_permlane16_swap_b32_e32 v231, v233
	global_store_dwordx4 v[234:235], v[226:229], off
	global_store_dwordx4 v[234:235], v[230:233], off offset:64
	v_lshl_add_u64 v[234:235], v[234:235], 0, v[236:237]
	global_load_dwordx4 v[210:213], v247, s[16:17]
	global_load_dwordx4 v[214:217], v247, s[16:17] offset:16
	v_add_u32_e32 v247, 0x400, v247
	v_add_f32_e32 v78, v78, v194
	v_add_f32_e32 v79, v79, v195
	v_add_f32_e32 v80, v80, v196
	v_add_f32_e32 v81, v81, v197
	v_add_f32_e32 v74, v74, v198
	v_add_f32_e32 v75, v75, v199
	v_add_f32_e32 v76, v76, v200
	v_add_f32_e32 v77, v77, v201
	v_add_f32_e32 v70, v70, v202
	v_add_f32_e32 v71, v71, v203
	v_add_f32_e32 v72, v72, v204
	v_add_f32_e32 v73, v73, v205
	v_add_f32_e32 v66, v66, v206
	v_add_f32_e32 v67, v67, v207
	v_add_f32_e32 v68, v68, v208
	v_add_f32_e32 v69, v69, v209
	v_mov_b32_e32 v238, v78
	v_mov_b32_e32 v239, v79
	v_mov_b32_e32 v240, v80
	v_mov_b32_e32 v241, v81
	v_permlane32_swap_b32_e32 v238, v78
	v_permlane32_swap_b32_e32 v239, v79
	v_permlane32_swap_b32_e32 v240, v80
	v_permlane32_swap_b32_e32 v241, v81
	s_waitcnt vmcnt(4)
	v_cndmask_b32_e64 v242, v238, -v78, s[12:13]
	v_cndmask_b32_e64 v238, v78, v238, s[12:13]
	v_cndmask_b32_e64 v243, v239, -v79, s[12:13]
	v_cndmask_b32_e64 v239, v79, v239, s[12:13]
	v_cndmask_b32_e64 v244, v240, -v80, s[12:13]
	v_cndmask_b32_e64 v240, v80, v240, s[12:13]
	v_cndmask_b32_e64 v245, v241, -v81, s[12:13]
	v_cndmask_b32_e64 v241, v81, v241, s[12:13]
	v_mul_f32_e32 v242, v242, v219
	v_mul_f32_e32 v243, v243, v221
	v_mul_f32_e32 v244, v244, v223
	v_mul_f32_e32 v245, v245, v225
	v_fma_f32 v78, v238, v218, v242
	v_fma_f32 v79, v239, v220, v243
	v_fma_f32 v80, v240, v222, v244
	v_fma_f32 v81, v241, v224, v245
	s_cmp_lg_u32 s7, 0
	s_cbranch_scc0 .Lqk_nc3
	global_store_dwordx4 v246, v[78:81], s[82:83] offset:0
	global_store_dwordx4 v246, v[74:77], s[82:83] offset:64
	global_store_dwordx4 v246, v[70:73], s[82:83] offset:128
	global_store_dwordx4 v246, v[66:69], s[82:83] offset:192
	v_add_u32_e32 v246, 0x4000, v246
.Lqk_nc3:
	v_cvt_pk_bf16_f32 v226, v78, v79
	v_cvt_pk_bf16_f32 v227, v80, v81
	v_cvt_pk_bf16_f32 v228, v74, v75
	v_cvt_pk_bf16_f32 v229, v76, v77
	v_cvt_pk_bf16_f32 v230, v70, v71
	v_cvt_pk_bf16_f32 v231, v72, v73
	v_cvt_pk_bf16_f32 v232, v66, v67
	v_cvt_pk_bf16_f32 v233, v68, v69
	s_nop 1
	v_permlane16_swap_b32_e32 v226, v228
	v_permlane16_swap_b32_e32 v227, v229
	v_permlane16_swap_b32_e32 v230, v232
	v_permlane16_swap_b32_e32 v231, v233
	global_store_dwordx4 v[234:235], v[226:229], off
	global_store_dwordx4 v[234:235], v[230:233], off offset:64
	v_lshl_add_u64 v[234:235], v[234:235], 0, v[236:237]
	global_load_dwordx4 v[218:221], v247, s[16:17]
	global_load_dwordx4 v[222:225], v247, s[16:17] offset:16
	v_add_u32_e32 v247, 0x400, v247
	v_add_f32_e32 v62, v62, v194
	v_add_f32_e32 v63, v63, v195
	v_add_f32_e32 v64, v64, v196
	v_add_f32_e32 v65, v65, v197
	v_add_f32_e32 v58, v58, v198
	v_add_f32_e32 v59, v59, v199
	v_add_f32_e32 v60, v60, v200
	v_add_f32_e32 v61, v61, v201
	v_add_f32_e32 v54, v54, v202
	v_add_f32_e32 v55, v55, v203
	v_add_f32_e32 v56, v56, v204
	v_add_f32_e32 v57, v57, v205
	v_add_f32_e32 v50, v50, v206
	v_add_f32_e32 v51, v51, v207
	v_add_f32_e32 v52, v52, v208
	v_add_f32_e32 v53, v53, v209
	v_mov_b32_e32 v238, v62
	v_mov_b32_e32 v239, v63
	v_mov_b32_e32 v240, v64
	v_mov_b32_e32 v241, v65
	v_permlane32_swap_b32_e32 v238, v62
	v_permlane32_swap_b32_e32 v239, v63
	v_permlane32_swap_b32_e32 v240, v64
	v_permlane32_swap_b32_e32 v241, v65
	s_waitcnt vmcnt(4)
	v_cndmask_b32_e64 v242, v238, -v62, s[12:13]
	v_cndmask_b32_e64 v238, v62, v238, s[12:13]
	v_cndmask_b32_e64 v243, v239, -v63, s[12:13]
	v_cndmask_b32_e64 v239, v63, v239, s[12:13]
	v_cndmask_b32_e64 v244, v240, -v64, s[12:13]
	v_cndmask_b32_e64 v240, v64, v240, s[12:13]
	v_cndmask_b32_e64 v245, v241, -v65, s[12:13]
	v_cndmask_b32_e64 v241, v65, v241, s[12:13]
	v_mul_f32_e32 v242, v242, v211
	v_mul_f32_e32 v243, v243, v213
	v_mul_f32_e32 v244, v244, v215
	v_mul_f32_e32 v245, v245, v217
	v_fma_f32 v62, v238, v210, v242
	v_fma_f32 v63, v239, v212, v243
	v_fma_f32 v64, v240, v214, v244
	v_fma_f32 v65, v241, v216, v245
	s_cmp_lg_u32 s7, 0
	s_cbranch_scc0 .Lqk_nc4
	global_store_dwordx4 v246, v[62:65], s[82:83] offset:0
	global_store_dwordx4 v246, v[58:61], s[82:83] offset:64
	global_store_dwordx4 v246, v[54:57], s[82:83] offset:128
	global_store_dwordx4 v246, v[50:53], s[82:83] offset:192
	v_add_u32_e32 v246, 0x4000, v246
.Lqk_nc4:
	v_cvt_pk_bf16_f32 v226, v62, v63
	v_cvt_pk_bf16_f32 v227, v64, v65
	v_cvt_pk_bf16_f32 v228, v58, v59
	v_cvt_pk_bf16_f32 v229, v60, v61
	v_cvt_pk_bf16_f32 v230, v54, v55
	v_cvt_pk_bf16_f32 v231, v56, v57
	v_cvt_pk_bf16_f32 v232, v50, v51
	v_cvt_pk_bf16_f32 v233, v52, v53
	s_nop 1
	v_permlane16_swap_b32_e32 v226, v228
	v_permlane16_swap_b32_e32 v227, v229
	v_permlane16_swap_b32_e32 v230, v232
	v_permlane16_swap_b32_e32 v231, v233
	global_store_dwordx4 v[234:235], v[226:229], off
	global_store_dwordx4 v[234:235], v[230:233], off offset:64
	v_lshl_add_u64 v[234:235], v[234:235], 0, v[236:237]
	global_load_dwordx4 v[210:213], v247, s[16:17]
	global_load_dwordx4 v[214:217], v247, s[16:17] offset:16
	v_add_u32_e32 v247, 0x400, v247
	v_add_f32_e32 v46, v46, v194
	v_add_f32_e32 v47, v47, v195
	v_add_f32_e32 v48, v48, v196
	v_add_f32_e32 v49, v49, v197
	v_add_f32_e32 v42, v42, v198
	v_add_f32_e32 v43, v43, v199
	v_add_f32_e32 v44, v44, v200
	v_add_f32_e32 v45, v45, v201
	v_add_f32_e32 v38, v38, v202
	v_add_f32_e32 v39, v39, v203
	v_add_f32_e32 v40, v40, v204
	v_add_f32_e32 v41, v41, v205
	v_add_f32_e32 v34, v34, v206
	v_add_f32_e32 v35, v35, v207
	v_add_f32_e32 v36, v36, v208
	v_add_f32_e32 v37, v37, v209
	v_mov_b32_e32 v238, v46
	v_mov_b32_e32 v239, v47
	v_mov_b32_e32 v240, v48
	v_mov_b32_e32 v241, v49
	v_permlane32_swap_b32_e32 v238, v46
	v_permlane32_swap_b32_e32 v239, v47
	v_permlane32_swap_b32_e32 v240, v48
	v_permlane32_swap_b32_e32 v241, v49
	s_waitcnt vmcnt(4)
	v_cndmask_b32_e64 v242, v238, -v46, s[12:13]
	v_cndmask_b32_e64 v238, v46, v238, s[12:13]
	v_cndmask_b32_e64 v243, v239, -v47, s[12:13]
	v_cndmask_b32_e64 v239, v47, v239, s[12:13]
	v_cndmask_b32_e64 v244, v240, -v48, s[12:13]
	v_cndmask_b32_e64 v240, v48, v240, s[12:13]
	v_cndmask_b32_e64 v245, v241, -v49, s[12:13]
	v_cndmask_b32_e64 v241, v49, v241, s[12:13]
	v_mul_f32_e32 v242, v242, v219
	v_mul_f32_e32 v243, v243, v221
	v_mul_f32_e32 v244, v244, v223
	v_mul_f32_e32 v245, v245, v225
	v_fma_f32 v46, v238, v218, v242
	v_fma_f32 v47, v239, v220, v243
	v_fma_f32 v48, v240, v222, v244
	v_fma_f32 v49, v241, v224, v245
	s_cmp_lg_u32 s7, 0
	s_cbranch_scc0 .Lqk_nc5
	global_store_dwordx4 v246, v[46:49], s[82:83] offset:0
	global_store_dwordx4 v246, v[42:45], s[82:83] offset:64
	global_store_dwordx4 v246, v[38:41], s[82:83] offset:128
	global_store_dwordx4 v246, v[34:37], s[82:83] offset:192
	v_add_u32_e32 v246, 0x4000, v246
.Lqk_nc5:
	v_cvt_pk_bf16_f32 v226, v46, v47
	v_cvt_pk_bf16_f32 v227, v48, v49
	v_cvt_pk_bf16_f32 v228, v42, v43
	v_cvt_pk_bf16_f32 v229, v44, v45
	v_cvt_pk_bf16_f32 v230, v38, v39
	v_cvt_pk_bf16_f32 v231, v40, v41
	v_cvt_pk_bf16_f32 v232, v34, v35
	v_cvt_pk_bf16_f32 v233, v36, v37
	s_nop 1
	v_permlane16_swap_b32_e32 v226, v228
	v_permlane16_swap_b32_e32 v227, v229
	v_permlane16_swap_b32_e32 v230, v232
	v_permlane16_swap_b32_e32 v231, v233
	global_store_dwordx4 v[234:235], v[226:229], off
	global_store_dwordx4 v[234:235], v[230:233], off offset:64
	v_lshl_add_u64 v[234:235], v[234:235], 0, v[236:237]
	global_load_dwordx4 v[218:221], v247, s[16:17]
	global_load_dwordx4 v[222:225], v247, s[16:17] offset:16
	v_add_u32_e32 v247, 0x400, v247
	v_add_f32_e32 v30, v30, v194
	v_add_f32_e32 v31, v31, v195
	v_add_f32_e32 v32, v32, v196
	v_add_f32_e32 v33, v33, v197
	v_add_f32_e32 v26, v26, v198
	v_add_f32_e32 v27, v27, v199
	v_add_f32_e32 v28, v28, v200
	v_add_f32_e32 v29, v29, v201
	v_add_f32_e32 v22, v22, v202
	v_add_f32_e32 v23, v23, v203
	v_add_f32_e32 v24, v24, v204
	v_add_f32_e32 v25, v25, v205
	v_add_f32_e32 v18, v18, v206
	v_add_f32_e32 v19, v19, v207
	v_add_f32_e32 v20, v20, v208
	v_add_f32_e32 v21, v21, v209
	v_mov_b32_e32 v238, v30
	v_mov_b32_e32 v239, v31
	v_mov_b32_e32 v240, v32
	v_mov_b32_e32 v241, v33
	v_permlane32_swap_b32_e32 v238, v30
	v_permlane32_swap_b32_e32 v239, v31
	v_permlane32_swap_b32_e32 v240, v32
	v_permlane32_swap_b32_e32 v241, v33
	s_waitcnt vmcnt(4)
	v_cndmask_b32_e64 v242, v238, -v30, s[12:13]
	v_cndmask_b32_e64 v238, v30, v238, s[12:13]
	v_cndmask_b32_e64 v243, v239, -v31, s[12:13]
	v_cndmask_b32_e64 v239, v31, v239, s[12:13]
	v_cndmask_b32_e64 v244, v240, -v32, s[12:13]
	v_cndmask_b32_e64 v240, v32, v240, s[12:13]
	v_cndmask_b32_e64 v245, v241, -v33, s[12:13]
	v_cndmask_b32_e64 v241, v33, v241, s[12:13]
	v_mul_f32_e32 v242, v242, v211
	v_mul_f32_e32 v243, v243, v213
	v_mul_f32_e32 v244, v244, v215
	v_mul_f32_e32 v245, v245, v217
	v_fma_f32 v30, v238, v210, v242
	v_fma_f32 v31, v239, v212, v243
	v_fma_f32 v32, v240, v214, v244
	v_fma_f32 v33, v241, v216, v245
	s_cmp_lg_u32 s7, 0
	s_cbranch_scc0 .Lqk_nc6
	global_store_dwordx4 v246, v[30:33], s[82:83] offset:0
	global_store_dwordx4 v246, v[26:29], s[82:83] offset:64
	global_store_dwordx4 v246, v[22:25], s[82:83] offset:128
	global_store_dwordx4 v246, v[18:21], s[82:83] offset:192
	v_add_u32_e32 v246, 0x4000, v246
.Lqk_nc6:
	v_cvt_pk_bf16_f32 v226, v30, v31
	v_cvt_pk_bf16_f32 v227, v32, v33
	v_cvt_pk_bf16_f32 v228, v26, v27
	v_cvt_pk_bf16_f32 v229, v28, v29
	v_cvt_pk_bf16_f32 v230, v22, v23
	v_cvt_pk_bf16_f32 v231, v24, v25
	v_cvt_pk_bf16_f32 v232, v18, v19
	v_cvt_pk_bf16_f32 v233, v20, v21
	s_nop 1
	v_permlane16_swap_b32_e32 v226, v228
	v_permlane16_swap_b32_e32 v227, v229
	v_permlane16_swap_b32_e32 v230, v232
	v_permlane16_swap_b32_e32 v231, v233
	global_store_dwordx4 v[234:235], v[226:229], off
	global_store_dwordx4 v[234:235], v[230:233], off offset:64
	v_lshl_add_u64 v[234:235], v[234:235], 0, v[236:237]
	v_add_f32_e32 v14, v14, v194
	v_add_f32_e32 v15, v15, v195
	v_add_f32_e32 v16, v16, v196
	v_add_f32_e32 v17, v17, v197
	v_add_f32_e32 v10, v10, v198
	v_add_f32_e32 v11, v11, v199
	v_add_f32_e32 v12, v12, v200
	v_add_f32_e32 v13, v13, v201
	v_add_f32_e32 v6, v6, v202
	v_add_f32_e32 v7, v7, v203
	v_add_f32_e32 v8, v8, v204
	v_add_f32_e32 v9, v9, v205
	v_add_f32_e32 v2, v2, v206
	v_add_f32_e32 v3, v3, v207
	v_add_f32_e32 v4, v4, v208
	v_add_f32_e32 v5, v5, v209
	v_mov_b32_e32 v238, v14
	v_mov_b32_e32 v239, v15
	v_mov_b32_e32 v240, v16
	v_mov_b32_e32 v241, v17
	v_permlane32_swap_b32_e32 v238, v14
	v_permlane32_swap_b32_e32 v239, v15
	v_permlane32_swap_b32_e32 v240, v16
	v_permlane32_swap_b32_e32 v241, v17
	s_waitcnt vmcnt(2)
	v_cndmask_b32_e64 v242, v238, -v14, s[12:13]
	v_cndmask_b32_e64 v238, v14, v238, s[12:13]
	v_cndmask_b32_e64 v243, v239, -v15, s[12:13]
	v_cndmask_b32_e64 v239, v15, v239, s[12:13]
	v_cndmask_b32_e64 v244, v240, -v16, s[12:13]
	v_cndmask_b32_e64 v240, v16, v240, s[12:13]
	v_cndmask_b32_e64 v245, v241, -v17, s[12:13]
	v_cndmask_b32_e64 v241, v17, v241, s[12:13]
	v_mul_f32_e32 v242, v242, v219
	v_mul_f32_e32 v243, v243, v221
	v_mul_f32_e32 v244, v244, v223
	v_mul_f32_e32 v245, v245, v225
	v_fma_f32 v14, v238, v218, v242
	v_fma_f32 v15, v239, v220, v243
	v_fma_f32 v16, v240, v222, v244
	v_fma_f32 v17, v241, v224, v245
	s_cmp_lg_u32 s7, 0
	s_cbranch_scc0 .Lqk_nc7
	global_store_dwordx4 v246, v[14:17], s[82:83] offset:0
	global_store_dwordx4 v246, v[10:13], s[82:83] offset:64
	global_store_dwordx4 v246, v[6:9], s[82:83] offset:128
	global_store_dwordx4 v246, v[2:5], s[82:83] offset:192
	v_add_u32_e32 v246, 0x4000, v246
.Lqk_nc7:
	v_cvt_pk_bf16_f32 v226, v14, v15
	v_cvt_pk_bf16_f32 v227, v16, v17
	v_cvt_pk_bf16_f32 v228, v10, v11
	v_cvt_pk_bf16_f32 v229, v12, v13
	v_cvt_pk_bf16_f32 v230, v6, v7
	v_cvt_pk_bf16_f32 v231, v8, v9
	v_cvt_pk_bf16_f32 v232, v2, v3
	v_cvt_pk_bf16_f32 v233, v4, v5
	s_nop 1
	v_permlane16_swap_b32_e32 v226, v228
	v_permlane16_swap_b32_e32 v227, v229
	v_permlane16_swap_b32_e32 v230, v232
	v_permlane16_swap_b32_e32 v231, v233
	global_store_dwordx4 v[234:235], v[226:229], off
	global_store_dwordx4 v[234:235], v[230:233], off offset:64
	s_mov_b64 s[10:11], exec
	s_branch .LBB0_1912
